# GEMM k-loops (inproj, ffn1, w_out, w_down): LDS-DMA pieces of the next tile issued B-operand first (the weight rows miss L2 more often), A pieces behind them
# baseline (speedup 1.0000x reference)
;     ...
; #pragma unroll 1
;     for (int kt = 0; kt < nk - 1; ++kt) {
;       asm volatile("s_waitcnt vmcnt(0) lgkmcnt(0)" ::: "memory");
;       __builtin_amdgcn_s_barrier();
;       asm volatile("" ::: "memory");
;       G3_STEP(kt, true)
;     }
.LBB0_37:
	s_lshl_b32 s11, s9, 1
	s_and_b32 s11, s11, 0x8000
	v_lshl_or_b32 v87, v86, 1, s11
	s_waitcnt vmcnt(0) lgkmcnt(0)
	s_barrier
	v_add3_u32 v100, v87, v84, v83
	v_add3_u32 v87, v87, v82, v83
	ds_read_b128 v[88:91], v100
	ds_read_b128 v[92:95], v100 offset:2048
	ds_read_b128 v[96:99], v100 offset:4096
	ds_read_b128 v[100:103], v100 offset:6144
	ds_read_b128 v[104:107], v87 offset:16384
	ds_read_b128 v[108:111], v87 offset:18432
	ds_read_b128 v[112:115], v87 offset:20480
	ds_read_b128 v[116:119], v87 offset:22528
	v_lshl_or_b32 v87, v85, 1, s11
	v_add3_u32 v132, v87, v84, v83
	v_add3_u32 v87, v87, v82, v83
	ds_read_b128 v[120:123], v132
	ds_read_b128 v[124:127], v132 offset:2048
	ds_read_b128 v[128:131], v132 offset:4096
	ds_read_b128 v[132:135], v132 offset:6144
	ds_read_b128 v[136:139], v87 offset:16384
	ds_read_b128 v[140:143], v87 offset:18432
	ds_read_b128 v[144:147], v87 offset:20480
	ds_read_b128 v[148:151], v87 offset:22528
	s_setprio 1
	s_andn2_b32 s11, 0x8000, s10
	s_waitcnt lgkmcnt(11)
	v_mfma_f32_16x16x32_bf16 v[60:63], v[88:91], v[104:107], v[60:63]
	s_add_i32 s11, s8, s11
	v_lshl_add_u64 v[172:173], v[76:77], 0, s[0:1]
	s_add_i32 s12, s11, 0x4000
	s_mov_b32 m0, s12
	s_nop 0
	global_load_lds_dwordx4 v[172:173], off
	s_waitcnt lgkmcnt(10)
	v_mfma_f32_16x16x32_bf16 v[56:59], v[88:91], v[108:111], v[56:59]
	v_lshl_add_u64 v[152:153], v[74:75], 0, s[0:1]
	v_lshl_add_u64 v[154:155], v[64:65], 0, s[0:1]
	v_lshl_add_u64 v[156:157], v[78:79], 0, s[0:1]
	v_lshl_add_u64 v[158:159], v[68:69], 0, s[0:1]
	v_lshl_add_u64 v[166:167], v[66:67], 0, s[0:1]
	v_lshl_add_u64 v[168:169], v[72:73], 0, s[0:1]
	v_lshl_add_u64 v[170:171], v[70:71], 0, s[0:1]
	s_waitcnt lgkmcnt(9)
	v_mfma_f32_16x16x32_bf16 v[52:55], v[88:91], v[112:115], v[52:55]
	s_add_i32 s12, s11, 0x4400
	s_mov_b32 m0, s12
	s_nop 0
	global_load_lds_dwordx4 v[168:169], off
	s_waitcnt lgkmcnt(8)
	v_mfma_f32_16x16x32_bf16 v[48:51], v[88:91], v[116:119], v[48:51]
	v_mfma_f32_16x16x32_bf16 v[44:47], v[92:95], v[104:107], v[44:47]
	s_add_i32 s12, s11, 0x4800
	s_mov_b32 m0, s12
	s_nop 0
	global_load_lds_dwordx4 v[156:157], off
	v_mfma_f32_16x16x32_bf16 v[40:43], v[92:95], v[108:111], v[40:43]
	v_mfma_f32_16x16x32_bf16 v[36:39], v[92:95], v[112:115], v[36:39]
	s_add_i32 s12, s11, 0x4c00
	s_mov_b32 m0, s12
	s_nop 0
	global_load_lds_dwordx4 v[166:167], off
	v_mfma_f32_16x16x32_bf16 v[32:35], v[92:95], v[116:119], v[32:35]
	v_mfma_f32_16x16x32_bf16 v[28:31], v[96:99], v[104:107], v[28:31]
	s_add_i32 s12, s11, 0
	s_mov_b32 m0, s12
	s_nop 0
	global_load_lds_dwordx4 v[154:155], off
	v_mfma_f32_16x16x32_bf16 v[24:27], v[96:99], v[108:111], v[24:27]
	v_mfma_f32_16x16x32_bf16 v[20:23], v[96:99], v[112:115], v[20:23]
	s_add_i32 s12, s11, 0x400
	s_mov_b32 m0, s12
	s_nop 0
	global_load_lds_dwordx4 v[158:159], off
	v_mfma_f32_16x16x32_bf16 v[16:19], v[96:99], v[116:119], v[16:19]
	v_mfma_f32_16x16x32_bf16 v[12:15], v[100:103], v[104:107], v[12:15]
	s_add_i32 s12, s11, 0x800
	s_mov_b32 m0, s12
	s_nop 0
	global_load_lds_dwordx4 v[152:153], off
	v_mfma_f32_16x16x32_bf16 v[8:11], v[100:103], v[108:111], v[8:11]
	v_mfma_f32_16x16x32_bf16 v[4:7], v[100:103], v[112:115], v[4:7]
	s_addk_i32 s11, 0xc00
	s_mov_b32 m0, s11
	s_nop 0
	global_load_lds_dwordx4 v[170:171], off
	v_mfma_f32_16x16x32_bf16 v[0:3], v[100:103], v[116:119], v[0:3]
	s_waitcnt lgkmcnt(3)
	v_mfma_f32_16x16x32_bf16 v[60:63], v[120:123], v[136:139], v[60:63]
	s_waitcnt lgkmcnt(2)
	v_mfma_f32_16x16x32_bf16 v[56:59], v[120:123], v[140:143], v[56:59]
	s_waitcnt lgkmcnt(1)
	v_mfma_f32_16x16x32_bf16 v[52:55], v[120:123], v[144:147], v[52:55]
	s_waitcnt lgkmcnt(0)
	v_mfma_f32_16x16x32_bf16 v[48:51], v[120:123], v[148:151], v[48:51]
	v_mfma_f32_16x16x32_bf16 v[44:47], v[124:127], v[136:139], v[44:47]
	v_mfma_f32_16x16x32_bf16 v[40:43], v[124:127], v[140:143], v[40:43]
	v_mfma_f32_16x16x32_bf16 v[36:39], v[124:127], v[144:147], v[36:39]
	v_mfma_f32_16x16x32_bf16 v[32:35], v[124:127], v[148:151], v[32:35]
	v_mfma_f32_16x16x32_bf16 v[28:31], v[128:131], v[136:139], v[28:31]
	v_mfma_f32_16x16x32_bf16 v[24:27], v[128:131], v[140:143], v[24:27]
	v_mfma_f32_16x16x32_bf16 v[20:23], v[128:131], v[144:147], v[20:23]
	v_mfma_f32_16x16x32_bf16 v[16:19], v[128:131], v[148:151], v[16:19]
	v_mfma_f32_16x16x32_bf16 v[12:15], v[132:135], v[136:139], v[12:15]
	v_mfma_f32_16x16x32_bf16 v[8:11], v[132:135], v[140:143], v[8:11]
	v_mfma_f32_16x16x32_bf16 v[4:7], v[132:135], v[144:147], v[4:7]
	v_mfma_f32_16x16x32_bf16 v[0:3], v[132:135], v[148:151], v[0:3]
	s_setprio 0
	s_add_i32 s10, s10, 0x8000
	s_add_u32 s0, s0, 0x80
	s_addc_u32 s1, s1, 0
	s_addk_i32 s9, 0x4000
	s_cmpk_lg_i32 s0, 0x1580
	s_cbranch_scc1 .LBB0_37
	v_lshlrev_b32_e32 v86, 1, v86
	v_lshlrev_b32_e32 v85, 1, v85
	s_waitcnt vmcnt(0) lgkmcnt(0)
	s_barrier
; DI void resid_tile(const u16* A, int K, const u16* Bt, const float* resid, float* out, int it, u16* sA, u16* sB) {
;     ...
;   float* sC = (float*)sA + w * (32 * 68);
; #pragma unroll
;   for (int hp = 0; hp < 2; ++hp) {
;     __syncthreads();
; #pragma unroll
;     for (int mi2 = 0; mi2 < 2; ++mi2)
; #pragma unroll
;       for (int ni = 0; ni < 4; ++ni)
; #pragma unroll
;         for (int j = 0; j < 4; ++j) sC[(16 * mi2 + 4 * quad + j) * 68 + 16 * ni + r16] = acc[2 * hp + mi2][ni][j];
;     __syncthreads();
; #pragma unroll
;     for (int q = 0; q < 8; ++q) {
;       const int c = lane + 64 * q, row = c >> 4, c4 = (c & 15) * 4;
;       const long o = ((long)mt * 128 + wm * 64 + 32 * hp + row) * DM + nt * 128 + wn * 64 + c4;
;       const float4 rv = *(const float4*)(resid + o);
	v_add3_u32 v76, v86, v84, v83
	v_add3_u32 v98, v86, v82, v83
	v_add3_u32 v84, v85, v84, v83
	v_add3_u32 v126, v85, v82, v83
	ds_read_b128 v[64:67], v76 offset:32768
	ds_read_b128 v[68:71], v76 offset:34816
	ds_read_b128 v[72:75], v76 offset:36864
	ds_read_b128 v[76:79], v76 offset:38912
	ds_read_b128 v[86:89], v98 offset:49152
	ds_read_b128 v[90:93], v98 offset:51200
	ds_read_b128 v[94:97], v98 offset:53248
	ds_read_b128 v[98:101], v98 offset:55296
	ds_read_b128 v[102:105], v84 offset:32768
	ds_read_b128 v[106:109], v84 offset:34816
	ds_read_b128 v[110:113], v84 offset:36864
	ds_read_b128 v[114:117], v84 offset:38912
	ds_read_b128 v[82:85], v126 offset:49152
	ds_read_b128 v[118:121], v126 offset:51200
	ds_read_b128 v[122:125], v126 offset:53248
	ds_read_b128 v[126:129], v126 offset:55296
	s_lshl_b64 s[0:1], s[2:3], 7
	v_and_b32_e32 v130, 15, v80
	s_setprio 1
	s_waitcnt lgkmcnt(11)
	v_mfma_f32_16x16x32_bf16 v[60:63], v[64:67], v[86:89], v[60:63]
	s_waitcnt lgkmcnt(10)
	v_mfma_f32_16x16x32_bf16 v[56:59], v[64:67], v[90:93], v[56:59]
	s_waitcnt lgkmcnt(9)
	v_mfma_f32_16x16x32_bf16 v[52:55], v[64:67], v[94:97], v[52:55]
	s_waitcnt lgkmcnt(8)
	v_mfma_f32_16x16x32_bf16 v[48:51], v[64:67], v[98:101], v[48:51]
	v_mfma_f32_16x16x32_bf16 v[44:47], v[68:71], v[86:89], v[44:47]
	v_mfma_f32_16x16x32_bf16 v[40:43], v[68:71], v[90:93], v[40:43]
	v_mfma_f32_16x16x32_bf16 v[36:39], v[68:71], v[94:97], v[36:39]
	v_mfma_f32_16x16x32_bf16 v[32:35], v[68:71], v[98:101], v[32:35]
	v_mfma_f32_16x16x32_bf16 v[28:31], v[72:75], v[86:89], v[28:31]
	v_mfma_f32_16x16x32_bf16 v[64:67], v[72:75], v[90:93], v[24:27]
	v_mfma_f32_16x16x32_bf16 v[20:23], v[72:75], v[94:97], v[20:23]
	v_mfma_f32_16x16x32_bf16 v[68:71], v[72:75], v[98:101], v[16:19]
	v_mfma_f32_16x16x32_bf16 v[12:15], v[76:79], v[86:89], v[12:15]
	v_mfma_f32_16x16x32_bf16 v[72:75], v[76:79], v[90:93], v[8:11]
	v_mfma_f32_16x16x32_bf16 v[4:7], v[76:79], v[94:97], v[4:7]
	v_mfma_f32_16x16x32_bf16 v[76:79], v[76:79], v[98:101], v[0:3]
	s_waitcnt lgkmcnt(3)
	v_mfma_f32_16x16x32_bf16 v[60:63], v[102:105], v[82:85], v[60:63]
	s_waitcnt lgkmcnt(2)
	v_mfma_f32_16x16x32_bf16 v[56:59], v[102:105], v[118:121], v[56:59]
	s_waitcnt lgkmcnt(1)
	v_mfma_f32_16x16x32_bf16 v[52:55], v[102:105], v[122:125], v[52:55]
	s_waitcnt lgkmcnt(0)
	v_mfma_f32_16x16x32_bf16 v[48:51], v[102:105], v[126:129], v[48:51]
	v_mfma_f32_16x16x32_bf16 v[44:47], v[106:109], v[82:85], v[44:47]
	v_mfma_f32_16x16x32_bf16 v[40:43], v[106:109], v[118:121], v[40:43]
	v_mfma_f32_16x16x32_bf16 v[36:39], v[106:109], v[122:125], v[36:39]
	v_mfma_f32_16x16x32_bf16 v[86:89], v[106:109], v[126:129], v[32:35]
	v_mfma_f32_16x16x32_bf16 v[24:27], v[110:113], v[82:85], v[28:31]
	v_mfma_f32_16x16x32_bf16 v[28:31], v[110:113], v[118:121], v[64:67]
	v_mfma_f32_16x16x32_bf16 v[16:19], v[110:113], v[122:125], v[20:23]
	v_mfma_f32_16x16x32_bf16 v[20:23], v[110:113], v[126:129], v[68:71]
	v_mfma_f32_16x16x32_bf16 v[8:11], v[114:117], v[82:85], v[12:15]
	v_mfma_f32_16x16x32_bf16 v[12:15], v[114:117], v[118:121], v[72:75]
	v_mfma_f32_16x16x32_bf16 v[0:3], v[114:117], v[122:125], v[4:7]
	v_mfma_f32_16x16x32_bf16 v[4:7], v[114:117], v[126:129], v[76:79]
	s_setprio 0
	v_lshrrev_b32_e32 v32, 2, v80
	v_and_b32_e32 v65, 12, v32
	v_lshlrev_b32_e32 v32, 2, v80
	v_and_b32_e32 v67, 60, v32
	v_ashrrev_i32_e32 v32, 1, v80
	v_and_b32_e32 v32, 0xffffffc0, v32
	v_ashrrev_i32_e32 v33, 31, v32
	v_mul_lo_u32 v64, v81, s18
	v_lshl_add_u64 v[32:33], s[0:1], 0, v[32:33]
	s_lshl_b32 s0, s7, 7
	v_and_b32_e32 v34, 64, v80
	v_lshl_or_b32 v66, v130, 2, v64
	s_ashr_i32 s1, s0, 31
	v_or3_b32 v34, s0, v34, v67
	s_movk_i32 s0, 0x110
	v_mad_u32_u24 v65, v65, s0, v66
	v_lshl_or_b32 v64, v67, 2, v64
	v_bfe_u32 v67, v80, 4, 2
	v_lshlrev_b32_e32 v175, 2, v34
	v_or3_b32 v174, v32, v67, 0
	v_lshl_add_u32 v90, v174, 12, v175
	global_load_dwordx4 v[106:109], v90, s[68:69] nt
	v_or3_b32 v174, v32, v67, 4
	v_lshl_add_u32 v91, v174, 12, v175
	global_load_dwordx4 v[110:113], v91, s[68:69] nt
	v_or3_b32 v174, v32, v67, 8
	v_lshl_add_u32 v92, v174, 12, v175
	global_load_dwordx4 v[114:117], v92, s[68:69] nt
	v_or3_b32 v174, v32, v67, 12
	v_lshl_add_u32 v93, v174, 12, v175
	global_load_dwordx4 v[118:121], v93, s[68:69] nt
	v_or3_b32 v174, v32, v67, 16
	v_lshl_add_u32 v94, v174, 12, v175
	global_load_dwordx4 v[122:125], v94, s[68:69] nt
	v_or3_b32 v174, v32, v67, 20
	v_lshl_add_u32 v95, v174, 12, v175
	global_load_dwordx4 v[126:129], v95, s[68:69] nt
	v_or3_b32 v174, v32, v67, 24
	v_lshl_add_u32 v96, v174, 12, v175
	global_load_dwordx4 v[130:133], v96, s[68:69] nt
	v_or3_b32 v174, v32, v67, 28
	v_lshl_add_u32 v97, v174, 12, v175
	global_load_dwordx4 v[134:137], v97, s[68:69] nt
	v_or3_b32 v174, v32, v67, 32
	v_lshl_add_u32 v98, v174, 12, v175
	global_load_dwordx4 v[210:213], v98, s[68:69] nt
	v_or3_b32 v174, v32, v67, 36
	v_lshl_add_u32 v99, v174, 12, v175
	global_load_dwordx4 v[214:217], v99, s[68:69] nt
	v_or3_b32 v174, v32, v67, 40
	v_lshl_add_u32 v100, v174, 12, v175
	global_load_dwordx4 v[218:221], v100, s[68:69] nt
	v_or3_b32 v174, v32, v67, 44
	v_lshl_add_u32 v101, v174, 12, v175
	global_load_dwordx4 v[222:225], v101, s[68:69] nt
	v_or3_b32 v174, v32, v67, 48
	v_lshl_add_u32 v102, v174, 12, v175
	global_load_dwordx4 v[226:229], v102, s[68:69] nt
	v_or3_b32 v174, v32, v67, 52
	v_lshl_add_u32 v103, v174, 12, v175
	global_load_dwordx4 v[230:233], v103, s[68:69] nt
	v_or3_b32 v174, v32, v67, 56
	v_lshl_add_u32 v104, v174, 12, v175
	global_load_dwordx4 v[234:237], v104, s[68:69] nt
	v_or3_b32 v174, v32, v67, 60
	v_lshl_add_u32 v105, v174, 12, v175
	global_load_dwordx4 v[238:241], v105, s[68:69] nt
	s_barrier
; DI void resid_tile(const u16* A, int K, const u16* Bt, const float* resid, float* out, int it, u16* sA, u16* sB) {
;     ...
;   float* sC = (float*)sA + w * (32 * 68);
; #pragma unroll
;   for (int hp = 0; hp < 2; ++hp) {
;     __syncthreads();
; #pragma unroll
;     for (int mi2 = 0; mi2 < 2; ++mi2)
; #pragma unroll
;       for (int ni = 0; ni < 4; ++ni)
; #pragma unroll
;         for (int j = 0; j < 4; ++j) sC[(16 * mi2 + 4 * quad + j) * 68 + 16 * ni + r16] = acc[2 * hp + mi2][ni][j];
;     __syncthreads();
; #pragma unroll
;     for (int q = 0; q < 8; ++q) {
;       const int c = lane + 64 * q, row = c >> 4, c4 = (c & 15) * 4;
;       const long o = ((long)mt * 128 + wm * 64 + 32 * hp + row) * DM + nt * 128 + wn * 64 + c4;
;       const float4 rv = *(const float4*)(resid + o);
;       const f32x4 cv = *(const f32x4*)(sC + row * 68 + c4);
;       *(float4*)(out + o) = make_float4(rv.x + cv[0], rv.y + cv[1], rv.z + cv[2], rv.w + cv[3]);
;     }
;   }
	ds_write2_b32 v65, v60, v56 offset1:16
	ds_write2_b32 v65, v61, v57 offset0:68 offset1:84
	ds_write2_b32 v65, v62, v58 offset0:136 offset1:152
	ds_write2_b32 v65, v63, v59 offset0:204 offset1:220
	ds_write2_b32 v65, v52, v48 offset0:32 offset1:48
	ds_write2_b32 v65, v53, v49 offset0:100 offset1:116
	ds_write2_b32 v65, v54, v50 offset0:168 offset1:184
	ds_write2_b32 v65, v55, v51 offset0:236 offset1:252
	v_add_u32_e32 v48, 0x1000, v65
	v_add_u32_e32 v49, 0x1400, v65
	ds_write2_b32 v48, v44, v40 offset0:64 offset1:80
	ds_write2_b32 v48, v45, v41 offset0:132 offset1:148
	ds_write2_b32 v48, v46, v42 offset0:200 offset1:216
	ds_write2_b32 v49, v47, v43 offset0:12 offset1:28
	ds_write2_b32 v48, v36, v86 offset0:96 offset1:112
	ds_write2_b32 v48, v37, v87 offset0:164 offset1:180
	ds_write2_b32 v48, v38, v88 offset0:232 offset1:248
	ds_write2_b32 v49, v39, v89 offset0:44 offset1:60
	s_waitcnt lgkmcnt(0)
	s_barrier
	v_mad_u32_u24 v36, v67, s0, v64
	ds_read_b128 v[40:43], v36
	ds_read_b128 v[44:47], v36 offset:1088
	ds_read_b128 v[52:55], v36 offset:2176
	ds_read_b128 v[56:59], v36 offset:3264
	ds_read_b128 v[60:63], v36 offset:4352
	ds_read_b128 v[68:71], v36 offset:5440
	ds_read_b128 v[72:75], v36 offset:6528
	ds_read_b128 v[76:79], v36 offset:7616
	s_add_i32 s4, s4, s6
	s_cmp_lt_i32 s4, s5
	s_waitcnt vmcnt(8) lgkmcnt(0)
	v_pk_add_f32 v[40:41], v[106:107], v[40:41]
	v_pk_add_f32 v[42:43], v[108:109], v[42:43]
	global_store_dwordx4 v90, v[40:43], s[68:69] sc1
	v_pk_add_f32 v[44:45], v[110:111], v[44:45]
	v_pk_add_f32 v[46:47], v[112:113], v[46:47]
	global_store_dwordx4 v91, v[44:47], s[68:69] sc1
	v_pk_add_f32 v[52:53], v[114:115], v[52:53]
	v_pk_add_f32 v[54:55], v[116:117], v[54:55]
	global_store_dwordx4 v92, v[52:55], s[68:69] sc1
	v_pk_add_f32 v[56:57], v[118:119], v[56:57]
	v_pk_add_f32 v[58:59], v[120:121], v[58:59]
	global_store_dwordx4 v93, v[56:59], s[68:69] sc1
	v_pk_add_f32 v[60:61], v[122:123], v[60:61]
	v_pk_add_f32 v[62:63], v[124:125], v[62:63]
	global_store_dwordx4 v94, v[60:63], s[68:69] sc1
	v_pk_add_f32 v[68:69], v[126:127], v[68:69]
	v_pk_add_f32 v[70:71], v[128:129], v[70:71]
	global_store_dwordx4 v95, v[68:71], s[68:69] sc1
	v_pk_add_f32 v[72:73], v[130:131], v[72:73]
	v_pk_add_f32 v[74:75], v[132:133], v[74:75]
	global_store_dwordx4 v96, v[72:75], s[68:69] sc1
	v_pk_add_f32 v[76:77], v[134:135], v[76:77]
	v_pk_add_f32 v[78:79], v[136:137], v[78:79]
	global_store_dwordx4 v97, v[76:79], s[68:69] sc1
	s_barrier
	ds_write2_b32 v65, v24, v28 offset1:16
	ds_write2_b32 v65, v25, v29 offset0:68 offset1:84
	ds_write2_b32 v65, v26, v30 offset0:136 offset1:152
	ds_write2_b32 v65, v27, v31 offset0:204 offset1:220
	ds_write2_b32 v65, v16, v20 offset0:32 offset1:48
	ds_write2_b32 v65, v17, v21 offset0:100 offset1:116
	ds_write2_b32 v65, v18, v22 offset0:168 offset1:184
	ds_write2_b32 v65, v19, v23 offset0:236 offset1:252
	ds_write2_b32 v48, v8, v12 offset0:64 offset1:80
	ds_write2_b32 v48, v9, v13 offset0:132 offset1:148
	ds_write2_b32 v48, v10, v14 offset0:200 offset1:216
	ds_write2_b32 v49, v11, v15 offset0:12 offset1:28
	ds_write2_b32 v48, v0, v4 offset0:96 offset1:112
	ds_write2_b32 v48, v1, v5 offset0:164 offset1:180
	ds_write2_b32 v48, v2, v6 offset0:232 offset1:248
	ds_write2_b32 v49, v3, v7 offset0:44 offset1:60
	s_waitcnt lgkmcnt(0)
	s_barrier
	ds_read_b128 v[0:3], v36
	ds_read_b128 v[4:7], v36 offset:1088
	ds_read_b128 v[8:11], v36 offset:2176
	ds_read_b128 v[12:15], v36 offset:3264
	ds_read_b128 v[16:19], v36 offset:4352
	ds_read_b128 v[20:23], v36 offset:5440
	ds_read_b128 v[24:27], v36 offset:6528
	ds_read_b128 v[28:31], v36 offset:7616
	s_waitcnt vmcnt(8) lgkmcnt(0)
	v_pk_add_f32 v[0:1], v[210:211], v[0:1]
	v_pk_add_f32 v[2:3], v[212:213], v[2:3]
	global_store_dwordx4 v98, v[0:3], s[68:69] sc1
	v_pk_add_f32 v[4:5], v[214:215], v[4:5]
	v_pk_add_f32 v[6:7], v[216:217], v[6:7]
	global_store_dwordx4 v99, v[4:7], s[68:69] sc1
	v_pk_add_f32 v[8:9], v[218:219], v[8:9]
	v_pk_add_f32 v[10:11], v[220:221], v[10:11]
	global_store_dwordx4 v100, v[8:11], s[68:69] sc1
	v_pk_add_f32 v[12:13], v[222:223], v[12:13]
	v_pk_add_f32 v[14:15], v[224:225], v[14:15]
	global_store_dwordx4 v101, v[12:15], s[68:69] sc1
	v_pk_add_f32 v[16:17], v[226:227], v[16:17]
	v_pk_add_f32 v[18:19], v[228:229], v[18:19]
	global_store_dwordx4 v102, v[16:19], s[68:69] sc1
	v_pk_add_f32 v[20:21], v[230:231], v[20:21]
	v_pk_add_f32 v[22:23], v[232:233], v[22:23]
	global_store_dwordx4 v103, v[20:23], s[68:69] sc1
	v_pk_add_f32 v[24:25], v[234:235], v[24:25]
	v_pk_add_f32 v[26:27], v[236:237], v[26:27]
	global_store_dwordx4 v104, v[24:27], s[68:69] sc1
	v_pk_add_f32 v[28:29], v[238:239], v[28:29]
	v_pk_add_f32 v[30:31], v[240:241], v[30:31]
	global_store_dwordx4 v105, v[28:31], s[68:69] sc1
	s_cbranch_scc1 .LBB0_36

;     ...
; #pragma unroll 1
;     for (int kt = 0; kt < nk - 1; ++kt) {
;       asm volatile("s_waitcnt vmcnt(0) lgkmcnt(0)" ::: "memory");
;       __builtin_amdgcn_s_barrier();
;       asm volatile("" ::: "memory");
;       G3_STEP(kt, true)
;     }
.LBB0_65:
	s_lshl_b32 s12, s3, 1
	s_and_b32 s12, s12, 0x8000
	v_lshl_or_b32 v87, v86, 1, s12
	s_waitcnt vmcnt(0) lgkmcnt(0)
	s_barrier
	v_add3_u32 v100, v87, v84, v83
	v_add3_u32 v87, v87, v82, v83
	ds_read_b128 v[88:91], v100
	ds_read_b128 v[92:95], v100 offset:2048
	ds_read_b128 v[96:99], v100 offset:4096
	ds_read_b128 v[100:103], v100 offset:6144
	ds_read_b128 v[104:107], v87 offset:16384
	ds_read_b128 v[108:111], v87 offset:18432
	ds_read_b128 v[112:115], v87 offset:20480
	ds_read_b128 v[116:119], v87 offset:22528
	v_lshl_or_b32 v87, v85, 1, s12
	v_add3_u32 v132, v87, v84, v83
	v_add3_u32 v87, v87, v82, v83
	ds_read_b128 v[120:123], v132
	ds_read_b128 v[124:127], v132 offset:2048
	ds_read_b128 v[128:131], v132 offset:4096
	ds_read_b128 v[132:135], v132 offset:6144
	ds_read_b128 v[136:139], v87 offset:16384
	ds_read_b128 v[140:143], v87 offset:18432
	ds_read_b128 v[144:147], v87 offset:20480
	ds_read_b128 v[148:151], v87 offset:22528
	s_setprio 1
	s_andn2_b32 s12, 0x8000, s11
	s_waitcnt lgkmcnt(11)
	v_mfma_f32_16x16x32_bf16 v[60:63], v[88:91], v[104:107], v[60:63]
	s_add_i32 s12, s1, s12
	v_lshl_add_u64 v[172:173], v[76:77], 0, s[6:7]
	s_add_i32 s13, s12, 0x4000
	s_mov_b32 m0, s13
	s_nop 0
	global_load_lds_dwordx4 v[172:173], off
	s_waitcnt lgkmcnt(10)
	v_mfma_f32_16x16x32_bf16 v[56:59], v[88:91], v[108:111], v[56:59]
	v_lshl_add_u64 v[152:153], v[74:75], 0, s[6:7]
	v_lshl_add_u64 v[154:155], v[64:65], 0, s[6:7]
	v_lshl_add_u64 v[156:157], v[78:79], 0, s[6:7]
	v_lshl_add_u64 v[158:159], v[68:69], 0, s[6:7]
	v_lshl_add_u64 v[166:167], v[66:67], 0, s[6:7]
	v_lshl_add_u64 v[168:169], v[72:73], 0, s[6:7]
	v_lshl_add_u64 v[170:171], v[70:71], 0, s[6:7]
	s_waitcnt lgkmcnt(9)
	v_mfma_f32_16x16x32_bf16 v[52:55], v[88:91], v[112:115], v[52:55]
	s_add_i32 s13, s12, 0x4400
	s_mov_b32 m0, s13
	s_nop 0
	global_load_lds_dwordx4 v[168:169], off
	s_waitcnt lgkmcnt(8)
	v_mfma_f32_16x16x32_bf16 v[48:51], v[88:91], v[116:119], v[48:51]
	v_mfma_f32_16x16x32_bf16 v[44:47], v[92:95], v[104:107], v[44:47]
	s_add_i32 s13, s12, 0x4800
	s_mov_b32 m0, s13
	s_nop 0
	global_load_lds_dwordx4 v[156:157], off
	v_mfma_f32_16x16x32_bf16 v[40:43], v[92:95], v[108:111], v[40:43]
	v_mfma_f32_16x16x32_bf16 v[36:39], v[92:95], v[112:115], v[36:39]
	s_add_i32 s13, s12, 0x4c00
	s_mov_b32 m0, s13
	s_nop 0
	global_load_lds_dwordx4 v[166:167], off
	v_mfma_f32_16x16x32_bf16 v[32:35], v[92:95], v[116:119], v[32:35]
	v_mfma_f32_16x16x32_bf16 v[28:31], v[96:99], v[104:107], v[28:31]
	s_add_i32 s13, s12, 0
	s_mov_b32 m0, s13
	s_nop 0
	global_load_lds_dwordx4 v[154:155], off
	v_mfma_f32_16x16x32_bf16 v[24:27], v[96:99], v[108:111], v[24:27]
	v_mfma_f32_16x16x32_bf16 v[20:23], v[96:99], v[112:115], v[20:23]
	s_add_i32 s13, s12, 0x400
	s_mov_b32 m0, s13
	s_nop 0
	global_load_lds_dwordx4 v[158:159], off
	v_mfma_f32_16x16x32_bf16 v[16:19], v[96:99], v[116:119], v[16:19]
	v_mfma_f32_16x16x32_bf16 v[12:15], v[100:103], v[104:107], v[12:15]
	s_add_i32 s13, s12, 0x800
	s_mov_b32 m0, s13
	s_nop 0
	global_load_lds_dwordx4 v[152:153], off
	v_mfma_f32_16x16x32_bf16 v[8:11], v[100:103], v[108:111], v[8:11]
	v_mfma_f32_16x16x32_bf16 v[4:7], v[100:103], v[112:115], v[4:7]
	s_addk_i32 s12, 0xc00
	s_mov_b32 m0, s12
	s_nop 0
	global_load_lds_dwordx4 v[170:171], off
	v_mfma_f32_16x16x32_bf16 v[0:3], v[100:103], v[116:119], v[0:3]
	s_waitcnt lgkmcnt(3)
	v_mfma_f32_16x16x32_bf16 v[60:63], v[120:123], v[136:139], v[60:63]
	s_waitcnt lgkmcnt(2)
	v_mfma_f32_16x16x32_bf16 v[56:59], v[120:123], v[140:143], v[56:59]
	s_waitcnt lgkmcnt(1)
	v_mfma_f32_16x16x32_bf16 v[52:55], v[120:123], v[144:147], v[52:55]
	s_waitcnt lgkmcnt(0)
	v_mfma_f32_16x16x32_bf16 v[48:51], v[120:123], v[148:151], v[48:51]
	v_mfma_f32_16x16x32_bf16 v[44:47], v[124:127], v[136:139], v[44:47]
	v_mfma_f32_16x16x32_bf16 v[40:43], v[124:127], v[140:143], v[40:43]
	v_mfma_f32_16x16x32_bf16 v[36:39], v[124:127], v[144:147], v[36:39]
	v_mfma_f32_16x16x32_bf16 v[32:35], v[124:127], v[148:151], v[32:35]
	v_mfma_f32_16x16x32_bf16 v[28:31], v[128:131], v[136:139], v[28:31]
	v_mfma_f32_16x16x32_bf16 v[24:27], v[128:131], v[140:143], v[24:27]
	v_mfma_f32_16x16x32_bf16 v[20:23], v[128:131], v[144:147], v[20:23]
	v_mfma_f32_16x16x32_bf16 v[16:19], v[128:131], v[148:151], v[16:19]
	v_mfma_f32_16x16x32_bf16 v[12:15], v[132:135], v[136:139], v[12:15]
	v_mfma_f32_16x16x32_bf16 v[8:11], v[132:135], v[140:143], v[8:11]
	v_mfma_f32_16x16x32_bf16 v[4:7], v[132:135], v[144:147], v[4:7]
	v_mfma_f32_16x16x32_bf16 v[0:3], v[132:135], v[148:151], v[0:3]
	s_setprio 0
	s_add_i32 s11, s11, 0x8000
	s_add_u32 s6, s6, 0x80
	s_addc_u32 s7, s7, 0
	s_addk_i32 s3, 0x4000
	s_cmpk_lg_i32 s6, 0x780
	s_cbranch_scc1 .LBB0_65
	v_lshlrev_b32_e32 v86, 1, v86
	v_lshlrev_b32_e32 v85, 1, v85
	s_waitcnt vmcnt(0) lgkmcnt(0)
	s_barrier
; DI float siluf_(float x) { return x * sigmoidf_(x); }
;     ...
; #pragma unroll 1
;     for (int kt = 0; kt < nk - 1; ++kt) {
;       asm volatile("s_waitcnt vmcnt(0) lgkmcnt(0)" ::: "memory");
;       __builtin_amdgcn_s_barrier();
;       asm volatile("" ::: "memory");
;       G3_STEP(kt, true)
;     }
;     asm volatile("s_waitcnt vmcnt(0) lgkmcnt(0)" ::: "memory");
;     __builtin_amdgcn_s_barrier();
;     asm volatile("" ::: "memory");
;     G3_STEP(nk - 1, false)
; DI void ffn1_tile(const Params& P, int l, int it, u16* sA, u16* sB) {
;     ...
;   __syncthreads();
; #pragma unroll
;   for (int mi = 0; mi < 4; ++mi)
; #pragma unroll
;     for (int ni = 0; ni < 2; ++ni)
; #pragma unroll
;       for (int j = 0; j < 4; ++j)
;         sA[(wm * 64 + 16 * mi + 4 * quad + j) * 72 + wn * 32 + 16 * ni + r16] = f2bf(siluf_(acc[mi][ni][j]) * acc[mi][ni + 2][j]);
	v_add3_u32 v76, v86, v84, v83
	v_add3_u32 v98, v86, v82, v83
	v_add3_u32 v84, v85, v84, v83
	v_add3_u32 v126, v85, v82, v83
	ds_read_b128 v[64:67], v76 offset:32768
	ds_read_b128 v[68:71], v76 offset:34816
	ds_read_b128 v[72:75], v76 offset:36864
	ds_read_b128 v[76:79], v76 offset:38912
	ds_read_b128 v[86:89], v98 offset:49152
	ds_read_b128 v[90:93], v98 offset:51200
	ds_read_b128 v[94:97], v98 offset:53248
	ds_read_b128 v[98:101], v98 offset:55296
	ds_read_b128 v[102:105], v84 offset:32768
	ds_read_b128 v[106:109], v84 offset:34816
	ds_read_b128 v[110:113], v84 offset:36864
	ds_read_b128 v[114:117], v84 offset:38912
	ds_read_b128 v[82:85], v126 offset:49152
	ds_read_b128 v[118:121], v126 offset:51200
	ds_read_b128 v[122:125], v126 offset:53248
	ds_read_b128 v[126:129], v126 offset:55296
	v_and_b32_e32 v138, 15, v80
	s_setprio 1
	s_waitcnt lgkmcnt(11)
	v_mfma_f32_16x16x32_bf16 v[60:63], v[64:67], v[86:89], v[60:63]
	s_waitcnt lgkmcnt(10)
	v_mfma_f32_16x16x32_bf16 v[56:59], v[64:67], v[90:93], v[56:59]
	s_waitcnt lgkmcnt(9)
	v_mfma_f32_16x16x32_bf16 v[52:55], v[64:67], v[94:97], v[52:55]
	s_waitcnt lgkmcnt(8)
	v_mfma_f32_16x16x32_bf16 v[64:67], v[64:67], v[98:101], v[48:51]
	v_mfma_f32_16x16x32_bf16 v[44:47], v[68:71], v[86:89], v[44:47]
	v_mfma_f32_16x16x32_bf16 v[130:133], v[68:71], v[90:93], v[40:43]
	v_mfma_f32_16x16x32_bf16 v[36:39], v[68:71], v[94:97], v[36:39]
	v_mfma_f32_16x16x32_bf16 v[68:71], v[68:71], v[98:101], v[32:35]
	v_mfma_f32_16x16x32_bf16 v[28:31], v[72:75], v[86:89], v[28:31]
	v_mfma_f32_16x16x32_bf16 v[134:137], v[72:75], v[90:93], v[24:27]
	v_mfma_f32_16x16x32_bf16 v[20:23], v[72:75], v[94:97], v[20:23]
	v_mfma_f32_16x16x32_bf16 v[72:75], v[72:75], v[98:101], v[16:19]
	v_mfma_f32_16x16x32_bf16 v[12:15], v[76:79], v[86:89], v[12:15]
	v_mfma_f32_16x16x32_bf16 v[86:89], v[76:79], v[90:93], v[8:11]
	v_mfma_f32_16x16x32_bf16 v[4:7], v[76:79], v[94:97], v[4:7]
	v_mfma_f32_16x16x32_bf16 v[76:79], v[76:79], v[98:101], v[0:3]
	s_waitcnt lgkmcnt(2)
	v_mfma_f32_16x16x32_bf16 v[0:3], v[114:117], v[118:121], v[86:89]
	v_mfma_f32_16x16x32_bf16 v[60:63], v[102:105], v[82:85], v[60:63]
	v_mfma_f32_16x16x32_bf16 v[48:51], v[102:105], v[118:121], v[56:59]
	s_waitcnt lgkmcnt(1)
	v_mfma_f32_16x16x32_bf16 v[90:93], v[102:105], v[122:125], v[52:55]
	s_waitcnt lgkmcnt(0)
	v_mfma_f32_16x16x32_bf16 v[52:55], v[102:105], v[126:129], v[64:67]
	v_mfma_f32_16x16x32_bf16 v[40:43], v[106:109], v[82:85], v[44:47]
	v_mfma_f32_16x16x32_bf16 v[32:35], v[106:109], v[118:121], v[130:133]
	v_mfma_f32_16x16x32_bf16 v[44:47], v[106:109], v[122:125], v[36:39]
	v_mfma_f32_16x16x32_bf16 v[36:39], v[106:109], v[126:129], v[68:71]
	v_mfma_f32_16x16x32_bf16 v[24:27], v[110:113], v[82:85], v[28:31]
	v_mfma_f32_16x16x32_bf16 v[16:19], v[110:113], v[118:121], v[134:137]
	v_mfma_f32_16x16x32_bf16 v[28:31], v[110:113], v[122:125], v[20:23]
	v_mfma_f32_16x16x32_bf16 v[20:23], v[110:113], v[126:129], v[72:75]
	v_mfma_f32_16x16x32_bf16 v[8:11], v[114:117], v[82:85], v[12:15]
	v_mfma_f32_16x16x32_bf16 v[12:15], v[114:117], v[122:125], v[4:7]
	v_mfma_f32_16x16x32_bf16 v[4:7], v[114:117], v[126:129], v[76:79]
	s_setprio 0
	v_lshrrev_b32_e32 v56, 2, v80
	v_and_b32_e32 v56, 12, v56
	s_mov_b32 s1, 0xfffffc0
	v_and_or_b32 v57, v81, s1, v56
	v_lshlrev_b32_e32 v56, 1, v138
	v_and_or_b32 v56, v80, 64, v56
	v_mad_u64_u32 v[56:57], s[6:7], v57, s54, v[56:57]
	v_mul_f32_e32 v57, 0xbfb8aa3b, v61
	v_exp_f32_e32 v57, v57
	s_barrier
	v_add_f32_e32 v57, 1.0, v57
	v_rcp_f32_e32 v57, v57
	v_mul_f32_e32 v58, 0xbfb8aa3b, v60
	v_exp_f32_e32 v58, v58
	s_add_u32 s1, s70, s4
	v_mul_f32_e32 v57, v61, v57
	v_mul_f32_e32 v57, v91, v57
	v_cvt_pk_bf16_f32 v57, v57, s0
	ds_write_b16 v56, v57 offset:144
	v_mul_f32_e32 v57, 0xbfb8aa3b, v62
	v_exp_f32_e32 v57, v57
	v_add_f32_e32 v58, 1.0, v58
	v_rcp_f32_e32 v58, v58
	s_addc_u32 s3, s71, s5
	v_add_f32_e32 v57, 1.0, v57
	v_rcp_f32_e32 v57, v57
	v_mul_f32_e32 v58, v60, v58
	s_mul_hi_i32 s4, s2, 0xb0000
	s_mul_i32 s2, s2, 0xb0000
	v_mul_f32_e32 v57, v62, v57
	v_mul_f32_e32 v57, v92, v57
	v_cvt_pk_bf16_f32 v57, v57, s0
	ds_write_b16 v56, v57 offset:288
	v_mul_f32_e32 v57, 0xbfb8aa3b, v63
	v_exp_f32_e32 v57, v57
	v_mul_f32_e32 v58, v90, v58
	s_add_u32 s2, s1, s2
	v_cvt_pk_bf16_f32 v58, v58, s0
	v_add_f32_e32 v57, 1.0, v57
	v_rcp_f32_e32 v57, v57
	s_addc_u32 s3, s3, s4
	ds_write_b16 v56, v58
	v_mul_f32_e32 v57, v63, v57
	v_mul_f32_e32 v57, v93, v57
	v_cvt_pk_bf16_f32 v57, v57, s0
	ds_write_b16 v56, v57 offset:432
	v_mul_f32_e32 v57, 0xbfb8aa3b, v48
	v_exp_f32_e32 v57, v57
	s_nop 0
	v_add_f32_e32 v57, 1.0, v57
	v_rcp_f32_e32 v57, v57
	s_nop 0
	v_mul_f32_e32 v48, v48, v57
	v_mul_f32_e32 v48, v52, v48
	v_cvt_pk_bf16_f32 v48, v48, s0
	ds_write_b16 v56, v48 offset:32
	v_mul_f32_e32 v48, 0xbfb8aa3b, v49
	v_exp_f32_e32 v48, v48
	s_nop 0
	v_add_f32_e32 v48, 1.0, v48
	v_rcp_f32_e32 v48, v48
	s_nop 0
	v_mul_f32_e32 v48, v49, v48
	v_mul_f32_e32 v48, v53, v48
	v_cvt_pk_bf16_f32 v48, v48, s0
	ds_write_b16 v56, v48 offset:176
	v_mul_f32_e32 v48, 0xbfb8aa3b, v50
	v_exp_f32_e32 v48, v48
	s_nop 0
	v_add_f32_e32 v48, 1.0, v48
	v_rcp_f32_e32 v48, v48
	s_nop 0
	v_mul_f32_e32 v48, v50, v48
	v_mul_f32_e32 v48, v54, v48
	v_cvt_pk_bf16_f32 v48, v48, s0
	ds_write_b16 v56, v48 offset:320
	v_mul_f32_e32 v48, 0xbfb8aa3b, v51
	v_exp_f32_e32 v48, v48
	s_nop 0
	v_add_f32_e32 v48, 1.0, v48
	v_rcp_f32_e32 v48, v48
	s_nop 0
	v_mul_f32_e32 v48, v51, v48
	v_mul_f32_e32 v48, v55, v48
	v_cvt_pk_bf16_f32 v48, v48, s0
	ds_write_b16 v56, v48 offset:464
	v_mul_f32_e32 v48, 0xbfb8aa3b, v40
	v_exp_f32_e32 v48, v48
	s_nop 0
	v_add_f32_e32 v48, 1.0, v48
	v_rcp_f32_e32 v48, v48
	s_nop 0
	v_mul_f32_e32 v40, v40, v48
; DI int TID() { int t = threadIdx.x; asm volatile("" : "+v"(t)); return t; }
; DI float siluf_(float x) { return x * sigmoidf_(x); }
; template <int NCOLS>
; DI void store_tile_bf16(const u16* sC, u16* gdst, long ld, int rows_valid) {
;   constexpr int CPR = NCOLS / 8, LS = NCOLS + 8;
;   const int tid = TID();
; #pragma unroll
;   for (int q = 0; q < (128 * CPR) / 256; ++q) {
;     const int c = tid + 256 * q, row = c / CPR, ch = c % CPR;
;     if (row < rows_valid) *(uint4*)(gdst + (long)row * ld + ch * 8) = *(const uint4*)(sC + row * LS + ch * 8);
;   }
; }
; DI void ffn1_tile(const Params& P, int l, int it, u16* sA, u16* sB) {
;     ...
;   for (int mi = 0; mi < 4; ++mi)
; #pragma unroll
;     for (int ni = 0; ni < 2; ++ni)
; #pragma unroll
;       for (int j = 0; j < 4; ++j)
;         sA[(wm * 64 + 16 * mi + 4 * quad + j) * 72 + wn * 32 + 16 * ni + r16] = f2bf(siluf_(acc[mi][ni][j]) * acc[mi][ni + 2][j]);
;   __syncthreads();
;   store_tile_bf16<64>(sA, ACT + (long)mt * 128 * DFF + nt * 64, DFF, 128);
	v_mul_f32_e32 v40, v44, v40
	v_cvt_pk_bf16_f32 v40, v40, s0
	ds_write_b16 v56, v40 offset:2304
	v_mul_f32_e32 v40, 0xbfb8aa3b, v41
	v_exp_f32_e32 v40, v40
	s_nop 0
	v_add_f32_e32 v40, 1.0, v40
	v_rcp_f32_e32 v40, v40
	s_nop 0
	v_mul_f32_e32 v40, v41, v40
	v_mul_f32_e32 v40, v45, v40
	v_cvt_pk_bf16_f32 v40, v40, s0
	ds_write_b16 v56, v40 offset:2448
	v_mul_f32_e32 v40, 0xbfb8aa3b, v42
	v_exp_f32_e32 v40, v40
	s_nop 0
	v_add_f32_e32 v40, 1.0, v40
	v_rcp_f32_e32 v40, v40
	s_nop 0
	v_mul_f32_e32 v40, v42, v40
	v_mul_f32_e32 v40, v46, v40
	v_cvt_pk_bf16_f32 v40, v40, s0
	ds_write_b16 v56, v40 offset:2592
	v_mul_f32_e32 v40, 0xbfb8aa3b, v43
	v_exp_f32_e32 v40, v40
	s_nop 0
	v_add_f32_e32 v40, 1.0, v40
	v_rcp_f32_e32 v40, v40
	s_nop 0
	v_mul_f32_e32 v40, v43, v40
	v_mul_f32_e32 v40, v47, v40
	v_cvt_pk_bf16_f32 v40, v40, s0
	ds_write_b16 v56, v40 offset:2736
	v_mul_f32_e32 v40, 0xbfb8aa3b, v32
	v_exp_f32_e32 v40, v40
	s_nop 0
	v_add_f32_e32 v40, 1.0, v40
	v_rcp_f32_e32 v40, v40
	s_nop 0
	v_mul_f32_e32 v32, v32, v40
	v_mul_f32_e32 v32, v36, v32
	v_cvt_pk_bf16_f32 v32, v32, s0
	ds_write_b16 v56, v32 offset:2336
	v_mul_f32_e32 v32, 0xbfb8aa3b, v33
	v_exp_f32_e32 v32, v32
	s_nop 0
	v_add_f32_e32 v32, 1.0, v32
	v_rcp_f32_e32 v32, v32
	s_nop 0
	v_mul_f32_e32 v32, v33, v32
	v_mul_f32_e32 v32, v37, v32
	v_cvt_pk_bf16_f32 v32, v32, s0
	ds_write_b16 v56, v32 offset:2480
	v_mul_f32_e32 v32, 0xbfb8aa3b, v34
	v_exp_f32_e32 v32, v32
	s_nop 0
	v_add_f32_e32 v32, 1.0, v32
	v_rcp_f32_e32 v32, v32
	s_nop 0
	v_mul_f32_e32 v32, v34, v32
	v_mul_f32_e32 v32, v38, v32
	v_cvt_pk_bf16_f32 v32, v32, s0
	ds_write_b16 v56, v32 offset:2624
	v_mul_f32_e32 v32, 0xbfb8aa3b, v35
	v_exp_f32_e32 v32, v32
	s_nop 0
	v_add_f32_e32 v32, 1.0, v32
	v_rcp_f32_e32 v32, v32
	s_nop 0
	v_mul_f32_e32 v32, v35, v32
	v_mul_f32_e32 v32, v39, v32
	v_cvt_pk_bf16_f32 v32, v32, s0
	ds_write_b16 v56, v32 offset:2768
	v_mul_f32_e32 v32, 0xbfb8aa3b, v24
	v_exp_f32_e32 v32, v32
	s_nop 0
	v_add_f32_e32 v32, 1.0, v32
	v_rcp_f32_e32 v32, v32
	s_nop 0
	v_mul_f32_e32 v24, v24, v32
	v_mul_f32_e32 v24, v28, v24
	v_cvt_pk_bf16_f32 v24, v24, s0
	ds_write_b16 v56, v24 offset:4608
	v_mul_f32_e32 v24, 0xbfb8aa3b, v25
	v_exp_f32_e32 v24, v24
	s_nop 0
	v_add_f32_e32 v24, 1.0, v24
	v_rcp_f32_e32 v24, v24
	s_nop 0
	v_mul_f32_e32 v24, v25, v24
	v_mul_f32_e32 v24, v29, v24
	v_cvt_pk_bf16_f32 v24, v24, s0
	ds_write_b16 v56, v24 offset:4752
	v_mul_f32_e32 v24, 0xbfb8aa3b, v26
	v_exp_f32_e32 v24, v24
	s_nop 0
	v_add_f32_e32 v24, 1.0, v24
	v_rcp_f32_e32 v24, v24
	s_nop 0
	v_mul_f32_e32 v24, v26, v24
	v_mul_f32_e32 v24, v30, v24
	v_cvt_pk_bf16_f32 v24, v24, s0
	ds_write_b16 v56, v24 offset:4896
	v_mul_f32_e32 v24, 0xbfb8aa3b, v27
	v_exp_f32_e32 v24, v24
	s_nop 0
	v_add_f32_e32 v24, 1.0, v24
	v_rcp_f32_e32 v24, v24
	s_nop 0
	v_mul_f32_e32 v24, v27, v24
	v_mul_f32_e32 v24, v31, v24
	v_cvt_pk_bf16_f32 v24, v24, s0
	ds_write_b16 v56, v24 offset:5040
	v_mul_f32_e32 v24, 0xbfb8aa3b, v16
	v_exp_f32_e32 v24, v24
	s_nop 0
	v_add_f32_e32 v24, 1.0, v24
	v_rcp_f32_e32 v24, v24
	s_nop 0
	v_mul_f32_e32 v16, v16, v24
	v_mul_f32_e32 v16, v20, v16
	v_cvt_pk_bf16_f32 v16, v16, s0
	ds_write_b16 v56, v16 offset:4640
	v_mul_f32_e32 v16, 0xbfb8aa3b, v17
	v_exp_f32_e32 v16, v16
	s_nop 0
	v_add_f32_e32 v16, 1.0, v16
	v_rcp_f32_e32 v16, v16
	s_nop 0
	v_mul_f32_e32 v16, v17, v16
	v_mul_f32_e32 v16, v21, v16
	v_cvt_pk_bf16_f32 v16, v16, s0
	ds_write_b16 v56, v16 offset:4784
	v_mul_f32_e32 v16, 0xbfb8aa3b, v18
	v_exp_f32_e32 v16, v16
	s_nop 0
	v_add_f32_e32 v16, 1.0, v16
	v_rcp_f32_e32 v16, v16
	s_nop 0
	v_mul_f32_e32 v16, v18, v16
	v_mul_f32_e32 v16, v22, v16
	v_cvt_pk_bf16_f32 v16, v16, s0
	ds_write_b16 v56, v16 offset:4928
	v_mul_f32_e32 v16, 0xbfb8aa3b, v19
	v_exp_f32_e32 v16, v16
	s_nop 0
	v_add_f32_e32 v16, 1.0, v16
	v_rcp_f32_e32 v16, v16
	s_nop 0
	v_mul_f32_e32 v16, v19, v16
	v_mul_f32_e32 v16, v23, v16
	v_cvt_pk_bf16_f32 v16, v16, s0
	ds_write_b16 v56, v16 offset:5072
	v_mul_f32_e32 v16, 0xbfb8aa3b, v8
	v_exp_f32_e32 v16, v16
	s_nop 0
	v_add_f32_e32 v16, 1.0, v16
	v_rcp_f32_e32 v16, v16
	s_nop 0
	v_mul_f32_e32 v8, v8, v16
	v_mul_f32_e32 v8, v12, v8
	v_cvt_pk_bf16_f32 v8, v8, s0
	ds_write_b16 v56, v8 offset:6912
	v_mul_f32_e32 v8, 0xbfb8aa3b, v9
	v_exp_f32_e32 v8, v8
	s_nop 0
	v_add_f32_e32 v8, 1.0, v8
	v_rcp_f32_e32 v8, v8
	s_nop 0
	v_mul_f32_e32 v8, v9, v8
	v_mul_f32_e32 v8, v13, v8
	v_cvt_pk_bf16_f32 v8, v8, s0
	ds_write_b16 v56, v8 offset:7056
	v_mul_f32_e32 v8, 0xbfb8aa3b, v10
	v_exp_f32_e32 v8, v8
	s_nop 0
	v_add_f32_e32 v8, 1.0, v8
	v_rcp_f32_e32 v8, v8
	s_nop 0
	v_mul_f32_e32 v8, v10, v8
	v_mul_f32_e32 v8, v14, v8
	v_cvt_pk_bf16_f32 v8, v8, s0
	ds_write_b16 v56, v8 offset:7200
	v_mul_f32_e32 v8, 0xbfb8aa3b, v11
	v_exp_f32_e32 v8, v8
	s_nop 0
	v_add_f32_e32 v8, 1.0, v8
	v_rcp_f32_e32 v8, v8
	s_nop 0
	v_mul_f32_e32 v8, v11, v8
	v_mul_f32_e32 v8, v15, v8
	v_cvt_pk_bf16_f32 v8, v8, s0
	ds_write_b16 v56, v8 offset:7344
	v_mul_f32_e32 v8, 0xbfb8aa3b, v0
	v_exp_f32_e32 v8, v8
	s_nop 0
	v_add_f32_e32 v8, 1.0, v8
	v_rcp_f32_e32 v8, v8
	s_nop 0
	v_mul_f32_e32 v0, v0, v8
	v_mul_f32_e32 v0, v4, v0
	v_cvt_pk_bf16_f32 v0, v0, s0
	ds_write_b16 v56, v0 offset:6944
	v_mul_f32_e32 v0, 0xbfb8aa3b, v1
	v_exp_f32_e32 v0, v0
	s_nop 0
	v_add_f32_e32 v0, 1.0, v0
	v_rcp_f32_e32 v0, v0
	s_nop 0
	v_mul_f32_e32 v0, v1, v0
	v_mul_f32_e32 v0, v5, v0
	v_cvt_pk_bf16_f32 v0, v0, s0
	ds_write_b16 v56, v0 offset:7088
	v_mul_f32_e32 v0, 0xbfb8aa3b, v2
	v_exp_f32_e32 v0, v0
	s_nop 0
	v_add_f32_e32 v0, 1.0, v0
	v_rcp_f32_e32 v0, v0
	s_nop 0
	v_mul_f32_e32 v0, v2, v0
	v_mul_f32_e32 v0, v6, v0
	v_cvt_pk_bf16_f32 v0, v0, s0
	ds_write_b16 v56, v0 offset:7232
	v_mul_f32_e32 v0, 0xbfb8aa3b, v3
	v_exp_f32_e32 v0, v0
	s_nop 0
	v_add_f32_e32 v0, 1.0, v0
	v_rcp_f32_e32 v0, v0
	s_nop 0
	v_mul_f32_e32 v0, v3, v0
	v_mul_f32_e32 v0, v7, v0
	v_cvt_pk_bf16_f32 v0, v0, s0
	s_lshl_b32 s0, s0, 6
	s_ashr_i32 s1, s0, 31
	s_lshl_b64 s[0:1], s[0:1], 1
	s_add_u32 s0, s2, s0
	s_addc_u32 s1, s3, s1
	ds_write_b16 v56, v0 offset:7376
	s_add_u32 s0, s0, 0x4000000
	v_mov_b32_e32 v0, v160
	s_movk_i32 s2, 0x400
	s_waitcnt lgkmcnt(0)
	s_barrier
	s_addc_u32 s1, s1, 0
	s_nop 0
	v_cmp_gt_i32_e32 vcc, s2, v0
	s_and_saveexec_b64 s[2:3], vcc
	s_cbranch_execz .LBB0_68
	v_ashrrev_i32_e32 v1, 31, v0
	v_lshrrev_b32_e32 v1, 29, v1
	v_add_u32_e32 v1, v0, v1
	v_ashrrev_i32_e32 v6, 3, v1
	v_and_b32_e32 v1, -8, v1
	v_sub_u32_e32 v1, v0, v1
	v_mul_lo_u32 v4, v6, s54
	v_lshlrev_b32_e32 v2, 3, v1
	v_lshl_add_u32 v1, v1, 4, v4
	v_mov_b64_e32 v[4:5], s[0:1]
	s_movk_i32 s4, 0x1600
	v_ashrrev_i32_e32 v3, 31, v2
	v_mad_i64_i32 v[4:5], s[4:5], v6, s4, v[4:5]
	v_lshl_add_u64 v[6:7], v[2:3], 1, v[4:5]
	ds_read_b128 v[2:5], v1
	s_waitcnt lgkmcnt(0)
	global_store_dwordx4 v[6:7], v[2:5], off sc1

;     ...
; #pragma unroll 1
;     for (int kt = 0; kt < nk - 1; ++kt) {
;       asm volatile("s_waitcnt vmcnt(0) lgkmcnt(0)" ::: "memory");
;       __builtin_amdgcn_s_barrier();
;       asm volatile("" ::: "memory");
;       G3_STEP(kt, true)
;     }
.LBB0_107:
	s_lshl_b32 s11, s9, 1
	s_and_b32 s11, s11, 0x8000
	v_lshl_or_b32 v87, v86, 1, s11
	s_waitcnt vmcnt(0) lgkmcnt(0)
	s_barrier
	v_add3_u32 v100, v87, v84, v83
	v_add3_u32 v87, v87, v82, v83
	ds_read_b128 v[88:91], v100
	ds_read_b128 v[92:95], v100 offset:2048
	ds_read_b128 v[96:99], v100 offset:4096
	ds_read_b128 v[100:103], v100 offset:6144
	ds_read_b128 v[104:107], v87 offset:16384
	ds_read_b128 v[108:111], v87 offset:18432
	ds_read_b128 v[112:115], v87 offset:20480
	ds_read_b128 v[116:119], v87 offset:22528
	v_lshl_or_b32 v87, v85, 1, s11
	v_add3_u32 v132, v87, v84, v83
	v_add3_u32 v87, v87, v82, v83
	ds_read_b128 v[120:123], v132
	ds_read_b128 v[124:127], v132 offset:2048
	ds_read_b128 v[128:131], v132 offset:4096
	ds_read_b128 v[132:135], v132 offset:6144
	ds_read_b128 v[136:139], v87 offset:16384
	ds_read_b128 v[140:143], v87 offset:18432
	ds_read_b128 v[144:147], v87 offset:20480
	ds_read_b128 v[148:151], v87 offset:22528
	s_setprio 1
	s_andn2_b32 s11, 0x8000, s10
	s_waitcnt lgkmcnt(11)
	v_mfma_f32_16x16x32_bf16 v[60:63], v[88:91], v[104:107], v[60:63]
	s_add_i32 s11, s1, s11
	v_lshl_add_u64 v[172:173], v[76:77], 0, s[2:3]
	s_add_i32 s12, s11, 0x4000
	s_mov_b32 m0, s12
	s_nop 0
	global_load_lds_dwordx4 v[172:173], off
	s_waitcnt lgkmcnt(10)
	v_mfma_f32_16x16x32_bf16 v[56:59], v[88:91], v[108:111], v[56:59]
	v_lshl_add_u64 v[152:153], v[74:75], 0, s[2:3]
	v_lshl_add_u64 v[154:155], v[64:65], 0, s[2:3]
	v_lshl_add_u64 v[156:157], v[78:79], 0, s[2:3]
	v_lshl_add_u64 v[158:159], v[68:69], 0, s[2:3]
	v_lshl_add_u64 v[166:167], v[66:67], 0, s[2:3]
	v_lshl_add_u64 v[168:169], v[72:73], 0, s[2:3]
	v_lshl_add_u64 v[170:171], v[70:71], 0, s[2:3]
	s_waitcnt lgkmcnt(9)
	v_mfma_f32_16x16x32_bf16 v[52:55], v[88:91], v[112:115], v[52:55]
	s_add_i32 s12, s11, 0x4400
	s_mov_b32 m0, s12
	s_nop 0
	global_load_lds_dwordx4 v[168:169], off
	s_waitcnt lgkmcnt(8)
	v_mfma_f32_16x16x32_bf16 v[48:51], v[88:91], v[116:119], v[48:51]
	v_mfma_f32_16x16x32_bf16 v[44:47], v[92:95], v[104:107], v[44:47]
	s_add_i32 s12, s11, 0x4800
	s_mov_b32 m0, s12
	s_nop 0
	global_load_lds_dwordx4 v[156:157], off
	v_mfma_f32_16x16x32_bf16 v[40:43], v[92:95], v[108:111], v[40:43]
	v_mfma_f32_16x16x32_bf16 v[36:39], v[92:95], v[112:115], v[36:39]
	s_add_i32 s12, s11, 0x4c00
	s_mov_b32 m0, s12
	s_nop 0
	global_load_lds_dwordx4 v[166:167], off
	v_mfma_f32_16x16x32_bf16 v[32:35], v[92:95], v[116:119], v[32:35]
	v_mfma_f32_16x16x32_bf16 v[28:31], v[96:99], v[104:107], v[28:31]
	s_add_i32 s12, s11, 0
	s_mov_b32 m0, s12
	s_nop 0
	global_load_lds_dwordx4 v[154:155], off
	v_mfma_f32_16x16x32_bf16 v[24:27], v[96:99], v[108:111], v[24:27]
	v_mfma_f32_16x16x32_bf16 v[20:23], v[96:99], v[112:115], v[20:23]
	s_add_i32 s12, s11, 0x400
	s_mov_b32 m0, s12
	s_nop 0
	global_load_lds_dwordx4 v[158:159], off
	v_mfma_f32_16x16x32_bf16 v[16:19], v[96:99], v[116:119], v[16:19]
	v_mfma_f32_16x16x32_bf16 v[12:15], v[100:103], v[104:107], v[12:15]
	s_add_i32 s12, s11, 0x800
	s_mov_b32 m0, s12
	s_nop 0
	global_load_lds_dwordx4 v[152:153], off
	v_mfma_f32_16x16x32_bf16 v[8:11], v[100:103], v[108:111], v[8:11]
	v_mfma_f32_16x16x32_bf16 v[4:7], v[100:103], v[112:115], v[4:7]
	s_addk_i32 s11, 0xc00
	s_mov_b32 m0, s11
	s_nop 0
	global_load_lds_dwordx4 v[170:171], off
	v_mfma_f32_16x16x32_bf16 v[0:3], v[100:103], v[116:119], v[0:3]
	s_waitcnt lgkmcnt(3)
	v_mfma_f32_16x16x32_bf16 v[60:63], v[120:123], v[136:139], v[60:63]
	s_waitcnt lgkmcnt(2)
	v_mfma_f32_16x16x32_bf16 v[56:59], v[120:123], v[140:143], v[56:59]
	s_waitcnt lgkmcnt(1)
	v_mfma_f32_16x16x32_bf16 v[52:55], v[120:123], v[144:147], v[52:55]
	s_waitcnt lgkmcnt(0)
	v_mfma_f32_16x16x32_bf16 v[48:51], v[120:123], v[148:151], v[48:51]
	v_mfma_f32_16x16x32_bf16 v[44:47], v[124:127], v[136:139], v[44:47]
	v_mfma_f32_16x16x32_bf16 v[40:43], v[124:127], v[140:143], v[40:43]
	v_mfma_f32_16x16x32_bf16 v[36:39], v[124:127], v[144:147], v[36:39]
	v_mfma_f32_16x16x32_bf16 v[32:35], v[124:127], v[148:151], v[32:35]
	v_mfma_f32_16x16x32_bf16 v[28:31], v[128:131], v[136:139], v[28:31]
	v_mfma_f32_16x16x32_bf16 v[24:27], v[128:131], v[140:143], v[24:27]
	v_mfma_f32_16x16x32_bf16 v[20:23], v[128:131], v[144:147], v[20:23]
	v_mfma_f32_16x16x32_bf16 v[16:19], v[128:131], v[148:151], v[16:19]
	v_mfma_f32_16x16x32_bf16 v[12:15], v[132:135], v[136:139], v[12:15]
	v_mfma_f32_16x16x32_bf16 v[8:11], v[132:135], v[140:143], v[8:11]
	v_mfma_f32_16x16x32_bf16 v[4:7], v[132:135], v[144:147], v[4:7]
	v_mfma_f32_16x16x32_bf16 v[0:3], v[132:135], v[148:151], v[0:3]
	s_setprio 0
	s_add_i32 s10, s10, 0x8000
	s_add_u32 s2, s2, 0x80
	s_addc_u32 s3, s3, 0
	s_addk_i32 s9, 0x4000
	s_cmpk_lg_i32 s2, 0x780
	s_cbranch_scc1 .LBB0_107
	v_lshlrev_b32_e32 v86, 1, v86
	v_lshlrev_b32_e32 v85, 1, v85
	s_waitcnt vmcnt(0) lgkmcnt(0)
	s_barrier
;     ...
; #pragma unroll 1
;     for (int kt = 0; kt < nk - 1; ++kt) {
;       asm volatile("s_waitcnt vmcnt(0) lgkmcnt(0)" ::: "memory");
;       __builtin_amdgcn_s_barrier();
;       asm volatile("" ::: "memory");
;       G3_STEP(kt, true)
;     }
;     asm volatile("s_waitcnt vmcnt(0) lgkmcnt(0)" ::: "memory");
;     __builtin_amdgcn_s_barrier();
;     asm volatile("" ::: "memory");
;     G3_STEP(nk - 1, false)
; DI void resid_tile(const u16* A, int K, const u16* Bt, const float* resid, float* out, int it, u16* sA, u16* sB) {
;     ...
;   float* sC = (float*)sA + w * (32 * 68);
; #pragma unroll
;   for (int hp = 0; hp < 2; ++hp) {
;     __syncthreads();
; #pragma unroll
;     for (int mi2 = 0; mi2 < 2; ++mi2)
; #pragma unroll
;       for (int ni = 0; ni < 4; ++ni)
; #pragma unroll
;         for (int j = 0; j < 4; ++j) sC[(16 * mi2 + 4 * quad + j) * 68 + 16 * ni + r16] = acc[2 * hp + mi2][ni][j];
;     __syncthreads();
; #pragma unroll
;     for (int q = 0; q < 8; ++q) {
;       const int c = lane + 64 * q, row = c >> 4, c4 = (c & 15) * 4;
;       const long o = ((long)mt * 128 + wm * 64 + 32 * hp + row) * DM + nt * 128 + wn * 64 + c4;
;       const float4 rv = *(const float4*)(resid + o);
	v_add3_u32 v76, v86, v84, v83
	v_add3_u32 v98, v86, v82, v83
	v_add3_u32 v84, v85, v84, v83
	v_add3_u32 v126, v85, v82, v83
	ds_read_b128 v[64:67], v76 offset:32768
	ds_read_b128 v[68:71], v76 offset:34816
	ds_read_b128 v[72:75], v76 offset:36864
	ds_read_b128 v[76:79], v76 offset:38912
	ds_read_b128 v[86:89], v98 offset:49152
	ds_read_b128 v[90:93], v98 offset:51200
	ds_read_b128 v[94:97], v98 offset:53248
	ds_read_b128 v[98:101], v98 offset:55296
	ds_read_b128 v[102:105], v84 offset:32768
	ds_read_b128 v[106:109], v84 offset:34816
	ds_read_b128 v[110:113], v84 offset:36864
	ds_read_b128 v[114:117], v84 offset:38912
	ds_read_b128 v[82:85], v126 offset:49152
	ds_read_b128 v[118:121], v126 offset:51200
	ds_read_b128 v[122:125], v126 offset:53248
	ds_read_b128 v[126:129], v126 offset:55296
	s_lshl_b64 s[2:3], s[4:5], 7
	v_and_b32_e32 v130, 15, v80
	s_setprio 1
	s_waitcnt lgkmcnt(11)
	v_mfma_f32_16x16x32_bf16 v[60:63], v[64:67], v[86:89], v[60:63]
	s_waitcnt lgkmcnt(10)
	v_mfma_f32_16x16x32_bf16 v[56:59], v[64:67], v[90:93], v[56:59]
	s_waitcnt lgkmcnt(9)
	v_mfma_f32_16x16x32_bf16 v[52:55], v[64:67], v[94:97], v[52:55]
	s_waitcnt lgkmcnt(8)
	v_mfma_f32_16x16x32_bf16 v[48:51], v[64:67], v[98:101], v[48:51]
	v_mfma_f32_16x16x32_bf16 v[44:47], v[68:71], v[86:89], v[44:47]
	v_mfma_f32_16x16x32_bf16 v[40:43], v[68:71], v[90:93], v[40:43]
	v_mfma_f32_16x16x32_bf16 v[36:39], v[68:71], v[94:97], v[36:39]
	v_mfma_f32_16x16x32_bf16 v[32:35], v[68:71], v[98:101], v[32:35]
	v_mfma_f32_16x16x32_bf16 v[28:31], v[72:75], v[86:89], v[28:31]
	v_mfma_f32_16x16x32_bf16 v[64:67], v[72:75], v[90:93], v[24:27]
	v_mfma_f32_16x16x32_bf16 v[20:23], v[72:75], v[94:97], v[20:23]
	v_mfma_f32_16x16x32_bf16 v[68:71], v[72:75], v[98:101], v[16:19]
	v_mfma_f32_16x16x32_bf16 v[12:15], v[76:79], v[86:89], v[12:15]
	v_mfma_f32_16x16x32_bf16 v[72:75], v[76:79], v[90:93], v[8:11]
	v_mfma_f32_16x16x32_bf16 v[4:7], v[76:79], v[94:97], v[4:7]
	v_mfma_f32_16x16x32_bf16 v[76:79], v[76:79], v[98:101], v[0:3]
	s_waitcnt lgkmcnt(3)
	v_mfma_f32_16x16x32_bf16 v[60:63], v[102:105], v[82:85], v[60:63]
	s_waitcnt lgkmcnt(2)
	v_mfma_f32_16x16x32_bf16 v[56:59], v[102:105], v[118:121], v[56:59]
	s_waitcnt lgkmcnt(1)
	v_mfma_f32_16x16x32_bf16 v[52:55], v[102:105], v[122:125], v[52:55]
	s_waitcnt lgkmcnt(0)
	v_mfma_f32_16x16x32_bf16 v[48:51], v[102:105], v[126:129], v[48:51]
	v_mfma_f32_16x16x32_bf16 v[44:47], v[106:109], v[82:85], v[44:47]
	v_mfma_f32_16x16x32_bf16 v[40:43], v[106:109], v[118:121], v[40:43]
	v_mfma_f32_16x16x32_bf16 v[36:39], v[106:109], v[122:125], v[36:39]
	v_mfma_f32_16x16x32_bf16 v[86:89], v[106:109], v[126:129], v[32:35]
	v_mfma_f32_16x16x32_bf16 v[24:27], v[110:113], v[82:85], v[28:31]
	v_mfma_f32_16x16x32_bf16 v[28:31], v[110:113], v[118:121], v[64:67]
	v_mfma_f32_16x16x32_bf16 v[16:19], v[110:113], v[122:125], v[20:23]
	v_mfma_f32_16x16x32_bf16 v[20:23], v[110:113], v[126:129], v[68:71]
	v_mfma_f32_16x16x32_bf16 v[8:11], v[114:117], v[82:85], v[12:15]
	v_mfma_f32_16x16x32_bf16 v[12:15], v[114:117], v[118:121], v[72:75]
	v_mfma_f32_16x16x32_bf16 v[0:3], v[114:117], v[122:125], v[4:7]
	v_mfma_f32_16x16x32_bf16 v[4:7], v[114:117], v[126:129], v[76:79]
	s_setprio 0
	v_lshrrev_b32_e32 v32, 2, v80
	v_and_b32_e32 v65, 12, v32
	v_lshlrev_b32_e32 v32, 2, v80
	v_mul_lo_u32 v64, v81, s16
	v_and_b32_e32 v67, 60, v32
	v_ashrrev_i32_e32 v32, 1, v80
	s_lshl_b32 s0, s0, 7
	v_and_b32_e32 v34, 64, v80
	v_lshl_or_b32 v66, v130, 2, v64
	v_and_b32_e32 v32, 0xffffffc0, v32
	s_ashr_i32 s1, s0, 31
	v_or3_b32 v34, s0, v34, v67
	s_movk_i32 s0, 0x110
	v_ashrrev_i32_e32 v33, 31, v32
	v_mad_u32_u24 v65, v65, s0, v66
	v_lshl_add_u64 v[32:33], s[2:3], 0, v[32:33]
	v_bfe_u32 v68, v80, 4, 2
	v_lshlrev_b32_e32 v175, 2, v34
	v_or3_b32 v174, v32, v68, 0
	v_lshl_add_u32 v90, v174, 12, v175
	global_load_dwordx4 v[106:109], v90, s[18:19] nt
	v_or3_b32 v174, v32, v68, 4
	v_lshl_add_u32 v91, v174, 12, v175
	global_load_dwordx4 v[110:113], v91, s[18:19] nt
	v_or3_b32 v174, v32, v68, 8
	v_lshl_add_u32 v92, v174, 12, v175
	global_load_dwordx4 v[114:117], v92, s[18:19] nt
	v_or3_b32 v174, v32, v68, 12
	v_lshl_add_u32 v93, v174, 12, v175
	global_load_dwordx4 v[118:121], v93, s[18:19] nt
	v_or3_b32 v174, v32, v68, 16
	v_lshl_add_u32 v94, v174, 12, v175
	global_load_dwordx4 v[122:125], v94, s[18:19] nt
	v_or3_b32 v174, v32, v68, 20
	v_lshl_add_u32 v95, v174, 12, v175
	global_load_dwordx4 v[126:129], v95, s[18:19] nt
	v_or3_b32 v174, v32, v68, 24
	v_lshl_add_u32 v96, v174, 12, v175
	global_load_dwordx4 v[130:133], v96, s[18:19] nt
	v_or3_b32 v174, v32, v68, 28
	v_lshl_add_u32 v97, v174, 12, v175
	global_load_dwordx4 v[134:137], v97, s[18:19] nt
	v_or3_b32 v174, v32, v68, 32
	v_lshl_add_u32 v98, v174, 12, v175
	global_load_dwordx4 v[210:213], v98, s[18:19] nt
	v_or3_b32 v174, v32, v68, 36
	v_lshl_add_u32 v99, v174, 12, v175
	global_load_dwordx4 v[214:217], v99, s[18:19] nt
	v_or3_b32 v174, v32, v68, 40
	v_lshl_add_u32 v100, v174, 12, v175
	global_load_dwordx4 v[218:221], v100, s[18:19] nt
	v_or3_b32 v174, v32, v68, 44
	v_lshl_add_u32 v101, v174, 12, v175
	global_load_dwordx4 v[222:225], v101, s[18:19] nt
	v_or3_b32 v174, v32, v68, 48
	v_lshl_add_u32 v102, v174, 12, v175
	global_load_dwordx4 v[226:229], v102, s[18:19] nt
	v_or3_b32 v174, v32, v68, 52
	v_lshl_add_u32 v103, v174, 12, v175
	global_load_dwordx4 v[230:233], v103, s[18:19] nt
	v_or3_b32 v174, v32, v68, 56
	v_lshl_add_u32 v104, v174, 12, v175
	global_load_dwordx4 v[234:237], v104, s[18:19] nt
	v_or3_b32 v174, v32, v68, 60
	v_lshl_add_u32 v105, v174, 12, v175
	global_load_dwordx4 v[238:241], v105, s[18:19] nt
	s_barrier
; DI void resid_tile(const u16* A, int K, const u16* Bt, const float* resid, float* out, int it, u16* sA, u16* sB) {
;     ...
;   float* sC = (float*)sA + w * (32 * 68);
; #pragma unroll
;   for (int hp = 0; hp < 2; ++hp) {
;     __syncthreads();
; #pragma unroll
;     for (int mi2 = 0; mi2 < 2; ++mi2)
; #pragma unroll
;       for (int ni = 0; ni < 4; ++ni)
; #pragma unroll
;         for (int j = 0; j < 4; ++j) sC[(16 * mi2 + 4 * quad + j) * 68 + 16 * ni + r16] = acc[2 * hp + mi2][ni][j];
;     __syncthreads();
; #pragma unroll
;     for (int q = 0; q < 8; ++q) {
;       const int c = lane + 64 * q, row = c >> 4, c4 = (c & 15) * 4;
;       const long o = ((long)mt * 128 + wm * 64 + 32 * hp + row) * DM + nt * 128 + wn * 64 + c4;
;       const float4 rv = *(const float4*)(resid + o);
;       const f32x4 cv = *(const f32x4*)(sC + row * 68 + c4);
;       *(float4*)(out + o) = make_float4(rv.x + cv[0], rv.y + cv[1], rv.z + cv[2], rv.w + cv[3]);
;     }
;   }
	ds_write2_b32 v65, v60, v56 offset1:16
	ds_write2_b32 v65, v61, v57 offset0:68 offset1:84
	ds_write2_b32 v65, v62, v58 offset0:136 offset1:152
	ds_write2_b32 v65, v63, v59 offset0:204 offset1:220
	ds_write2_b32 v65, v52, v48 offset0:32 offset1:48
	ds_write2_b32 v65, v53, v49 offset0:100 offset1:116
	ds_write2_b32 v65, v54, v50 offset0:168 offset1:184
	ds_write2_b32 v65, v55, v51 offset0:236 offset1:252
	v_add_u32_e32 v54, 0x1000, v65
	v_add_u32_e32 v55, 0x1400, v65
	ds_write2_b32 v54, v44, v40 offset0:64 offset1:80
	ds_write2_b32 v54, v45, v41 offset0:132 offset1:148
	ds_write2_b32 v54, v46, v42 offset0:200 offset1:216
	ds_write2_b32 v55, v47, v43 offset0:12 offset1:28
	ds_write2_b32 v54, v36, v86 offset0:96 offset1:112
	ds_write2_b32 v54, v37, v87 offset0:164 offset1:180
	ds_write2_b32 v54, v38, v88 offset0:232 offset1:248
	ds_write2_b32 v55, v39, v89 offset0:44 offset1:60
	s_waitcnt lgkmcnt(0)
	s_barrier
	v_lshl_or_b32 v40, v67, 2, v64
	v_mad_u32_u24 v57, v68, s0, v40
	ds_read_b128 v[36:39], v57
	ds_read_b128 v[40:43], v57 offset:1088
	ds_read_b128 v[44:47], v57 offset:2176
	ds_read_b128 v[48:51], v57 offset:3264
	ds_read_b128 v[60:63], v57 offset:4352
	ds_read_b128 v[72:75], v57 offset:5440
	ds_read_b128 v[76:79], v57 offset:6528
	ds_read_b128 v[174:177], v57 offset:7616
	s_add_i32 s6, s6, s8
	s_cmp_ge_i32 s6, s7
	s_waitcnt vmcnt(8) lgkmcnt(0)
	v_pk_add_f32 v[36:37], v[106:107], v[36:37]
	v_pk_add_f32 v[38:39], v[108:109], v[38:39]
	global_store_dwordx4 v90, v[36:39], s[68:69] sc1
	v_pk_add_f32 v[40:41], v[110:111], v[40:41]
	v_pk_add_f32 v[42:43], v[112:113], v[42:43]
	global_store_dwordx4 v91, v[40:43], s[68:69] sc1
	v_pk_add_f32 v[44:45], v[114:115], v[44:45]
	v_pk_add_f32 v[46:47], v[116:117], v[46:47]
	global_store_dwordx4 v92, v[44:47], s[68:69] sc1
	v_pk_add_f32 v[48:49], v[118:119], v[48:49]
	v_pk_add_f32 v[50:51], v[120:121], v[50:51]
	global_store_dwordx4 v93, v[48:51], s[68:69] sc1
	v_pk_add_f32 v[60:61], v[122:123], v[60:61]
	v_pk_add_f32 v[62:63], v[124:125], v[62:63]
	global_store_dwordx4 v94, v[60:63], s[68:69] sc1
	v_pk_add_f32 v[72:73], v[126:127], v[72:73]
	v_pk_add_f32 v[74:75], v[128:129], v[74:75]
	global_store_dwordx4 v95, v[72:75], s[68:69] sc1
	v_pk_add_f32 v[76:77], v[130:131], v[76:77]
	v_pk_add_f32 v[78:79], v[132:133], v[78:79]
	global_store_dwordx4 v96, v[76:79], s[68:69] sc1
	v_pk_add_f32 v[174:175], v[134:135], v[174:175]
	v_pk_add_f32 v[176:177], v[136:137], v[176:177]
	global_store_dwordx4 v97, v[174:177], s[68:69] sc1
	s_barrier
	ds_write2_b32 v65, v24, v28 offset1:16
	ds_write2_b32 v65, v25, v29 offset0:68 offset1:84
	ds_write2_b32 v65, v26, v30 offset0:136 offset1:152
	ds_write2_b32 v65, v27, v31 offset0:204 offset1:220
	ds_write2_b32 v65, v16, v20 offset0:32 offset1:48
	ds_write2_b32 v65, v17, v21 offset0:100 offset1:116
	ds_write2_b32 v65, v18, v22 offset0:168 offset1:184
	ds_write2_b32 v65, v19, v23 offset0:236 offset1:252
	ds_write2_b32 v54, v8, v12 offset0:64 offset1:80
	ds_write2_b32 v54, v9, v13 offset0:132 offset1:148
	ds_write2_b32 v54, v10, v14 offset0:200 offset1:216
	ds_write2_b32 v55, v11, v15 offset0:12 offset1:28
	ds_write2_b32 v54, v0, v4 offset0:96 offset1:112
	ds_write2_b32 v54, v1, v5 offset0:164 offset1:180
	ds_write2_b32 v54, v2, v6 offset0:232 offset1:248
	ds_write2_b32 v55, v3, v7 offset0:44 offset1:60
	s_waitcnt lgkmcnt(0)
	s_barrier
	ds_read_b128 v[0:3], v57
	ds_read_b128 v[4:7], v57 offset:1088
	ds_read_b128 v[8:11], v57 offset:2176
	ds_read_b128 v[12:15], v57 offset:3264
	ds_read_b128 v[16:19], v57 offset:4352
	ds_read_b128 v[20:23], v57 offset:5440
	ds_read_b128 v[24:27], v57 offset:6528
	ds_read_b128 v[28:31], v57 offset:7616
	s_waitcnt vmcnt(8) lgkmcnt(0)
	v_pk_add_f32 v[0:1], v[210:211], v[0:1]
	v_pk_add_f32 v[2:3], v[212:213], v[2:3]
	global_store_dwordx4 v98, v[0:3], s[68:69] sc1
	v_pk_add_f32 v[4:5], v[214:215], v[4:5]
	v_pk_add_f32 v[6:7], v[216:217], v[6:7]
	global_store_dwordx4 v99, v[4:7], s[68:69] sc1
	v_pk_add_f32 v[8:9], v[218:219], v[8:9]
	v_pk_add_f32 v[10:11], v[220:221], v[10:11]
	global_store_dwordx4 v100, v[8:11], s[68:69] sc1
	v_pk_add_f32 v[12:13], v[222:223], v[12:13]
	v_pk_add_f32 v[14:15], v[224:225], v[14:15]
	global_store_dwordx4 v101, v[12:15], s[68:69] sc1
	v_pk_add_f32 v[16:17], v[226:227], v[16:17]
	v_pk_add_f32 v[18:19], v[228:229], v[18:19]
	global_store_dwordx4 v102, v[16:19], s[68:69] sc1
	v_pk_add_f32 v[20:21], v[230:231], v[20:21]
	v_pk_add_f32 v[22:23], v[232:233], v[22:23]
	global_store_dwordx4 v103, v[20:23], s[68:69] sc1
	v_pk_add_f32 v[24:25], v[234:235], v[24:25]
	v_pk_add_f32 v[26:27], v[236:237], v[26:27]
	global_store_dwordx4 v104, v[24:27], s[68:69] sc1
	v_pk_add_f32 v[28:29], v[238:239], v[28:29]
	v_pk_add_f32 v[30:31], v[240:241], v[30:31]
	global_store_dwordx4 v105, v[28:31], s[68:69] sc1
	s_cbranch_scc0 .LBB0_106

;     ...
; #pragma unroll 1
;     for (int kt = 0; kt < nk - 1; ++kt) {
;       asm volatile("s_waitcnt vmcnt(0) lgkmcnt(0)" ::: "memory");
;       __builtin_amdgcn_s_barrier();
;       asm volatile("" ::: "memory");
;       G3_STEP(kt, true)
;     }
.LBB0_660:
	s_lshl_b32 s12, s3, 1
	s_and_b32 s12, s12, 0x8000
	v_lshl_or_b32 v87, v86, 1, s12
	s_waitcnt vmcnt(0) lgkmcnt(0)
	s_barrier
	v_add3_u32 v100, v87, v84, v83
	v_add3_u32 v87, v87, v82, v83
	ds_read_b128 v[88:91], v100
	ds_read_b128 v[92:95], v100 offset:2048
	ds_read_b128 v[96:99], v100 offset:4096
	ds_read_b128 v[100:103], v100 offset:6144
	ds_read_b128 v[104:107], v87 offset:16384
	ds_read_b128 v[108:111], v87 offset:18432
	ds_read_b128 v[112:115], v87 offset:20480
	ds_read_b128 v[116:119], v87 offset:22528
	v_lshl_or_b32 v87, v85, 1, s12
	v_add3_u32 v132, v87, v84, v83
	v_add3_u32 v87, v87, v82, v83
	ds_read_b128 v[120:123], v132
	ds_read_b128 v[124:127], v132 offset:2048
	ds_read_b128 v[128:131], v132 offset:4096
	ds_read_b128 v[132:135], v132 offset:6144
	ds_read_b128 v[136:139], v87 offset:16384
	ds_read_b128 v[140:143], v87 offset:18432
	ds_read_b128 v[144:147], v87 offset:20480
	ds_read_b128 v[148:151], v87 offset:22528
	s_setprio 1
	s_andn2_b32 s12, 0x8000, s11
	s_waitcnt lgkmcnt(11)
	v_mfma_f32_16x16x32_bf16 v[60:63], v[88:91], v[104:107], v[60:63]
	s_add_i32 s12, s1, s12
	v_lshl_add_u64 v[172:173], v[76:77], 0, s[6:7]
	s_add_i32 s13, s12, 0x4000
	s_mov_b32 m0, s13
	s_nop 0
	global_load_lds_dwordx4 v[172:173], off
	s_waitcnt lgkmcnt(10)
	v_mfma_f32_16x16x32_bf16 v[56:59], v[88:91], v[108:111], v[56:59]
	v_lshl_add_u64 v[152:153], v[74:75], 0, s[6:7]
	v_lshl_add_u64 v[154:155], v[64:65], 0, s[6:7]
	v_lshl_add_u64 v[156:157], v[78:79], 0, s[6:7]
	v_lshl_add_u64 v[158:159], v[68:69], 0, s[6:7]
	v_lshl_add_u64 v[166:167], v[66:67], 0, s[6:7]
	v_lshl_add_u64 v[168:169], v[72:73], 0, s[6:7]
	v_lshl_add_u64 v[170:171], v[70:71], 0, s[6:7]
	s_waitcnt lgkmcnt(9)
	v_mfma_f32_16x16x32_bf16 v[52:55], v[88:91], v[112:115], v[52:55]
	s_add_i32 s13, s12, 0x4400
	s_mov_b32 m0, s13
	s_nop 0
	global_load_lds_dwordx4 v[168:169], off
	s_waitcnt lgkmcnt(8)
	v_mfma_f32_16x16x32_bf16 v[48:51], v[88:91], v[116:119], v[48:51]
	v_mfma_f32_16x16x32_bf16 v[44:47], v[92:95], v[104:107], v[44:47]
	s_add_i32 s13, s12, 0x4800
	s_mov_b32 m0, s13
	s_nop 0
	global_load_lds_dwordx4 v[156:157], off
	v_mfma_f32_16x16x32_bf16 v[40:43], v[92:95], v[108:111], v[40:43]
	v_mfma_f32_16x16x32_bf16 v[36:39], v[92:95], v[112:115], v[36:39]
	s_add_i32 s13, s12, 0x4c00
	s_mov_b32 m0, s13
	s_nop 0
	global_load_lds_dwordx4 v[166:167], off
	v_mfma_f32_16x16x32_bf16 v[32:35], v[92:95], v[116:119], v[32:35]
	v_mfma_f32_16x16x32_bf16 v[28:31], v[96:99], v[104:107], v[28:31]
	s_add_i32 s13, s12, 0
	s_mov_b32 m0, s13
	s_nop 0
	global_load_lds_dwordx4 v[154:155], off
	v_mfma_f32_16x16x32_bf16 v[24:27], v[96:99], v[108:111], v[24:27]
	v_mfma_f32_16x16x32_bf16 v[20:23], v[96:99], v[112:115], v[20:23]
	s_add_i32 s13, s12, 0x400
	s_mov_b32 m0, s13
	s_nop 0
	global_load_lds_dwordx4 v[158:159], off
	v_mfma_f32_16x16x32_bf16 v[16:19], v[96:99], v[116:119], v[16:19]
	v_mfma_f32_16x16x32_bf16 v[12:15], v[100:103], v[104:107], v[12:15]
	s_add_i32 s13, s12, 0x800
	s_mov_b32 m0, s13
	s_nop 0
	global_load_lds_dwordx4 v[152:153], off
	v_mfma_f32_16x16x32_bf16 v[8:11], v[100:103], v[108:111], v[8:11]
	v_mfma_f32_16x16x32_bf16 v[4:7], v[100:103], v[112:115], v[4:7]
	s_addk_i32 s12, 0xc00
	s_mov_b32 m0, s12
	s_nop 0
	global_load_lds_dwordx4 v[170:171], off
	v_mfma_f32_16x16x32_bf16 v[0:3], v[100:103], v[116:119], v[0:3]
	s_waitcnt lgkmcnt(3)
	v_mfma_f32_16x16x32_bf16 v[60:63], v[120:123], v[136:139], v[60:63]
	s_waitcnt lgkmcnt(2)
	v_mfma_f32_16x16x32_bf16 v[56:59], v[120:123], v[140:143], v[56:59]
	s_waitcnt lgkmcnt(1)
	v_mfma_f32_16x16x32_bf16 v[52:55], v[120:123], v[144:147], v[52:55]
	s_waitcnt lgkmcnt(0)
	v_mfma_f32_16x16x32_bf16 v[48:51], v[120:123], v[148:151], v[48:51]
	v_mfma_f32_16x16x32_bf16 v[44:47], v[124:127], v[136:139], v[44:47]
	v_mfma_f32_16x16x32_bf16 v[40:43], v[124:127], v[140:143], v[40:43]
	v_mfma_f32_16x16x32_bf16 v[36:39], v[124:127], v[144:147], v[36:39]
	v_mfma_f32_16x16x32_bf16 v[32:35], v[124:127], v[148:151], v[32:35]
	v_mfma_f32_16x16x32_bf16 v[28:31], v[128:131], v[136:139], v[28:31]
	v_mfma_f32_16x16x32_bf16 v[24:27], v[128:131], v[140:143], v[24:27]
	v_mfma_f32_16x16x32_bf16 v[20:23], v[128:131], v[144:147], v[20:23]
	v_mfma_f32_16x16x32_bf16 v[16:19], v[128:131], v[148:151], v[16:19]
	v_mfma_f32_16x16x32_bf16 v[12:15], v[132:135], v[136:139], v[12:15]
	v_mfma_f32_16x16x32_bf16 v[8:11], v[132:135], v[140:143], v[8:11]
	v_mfma_f32_16x16x32_bf16 v[4:7], v[132:135], v[144:147], v[4:7]
	v_mfma_f32_16x16x32_bf16 v[0:3], v[132:135], v[148:151], v[0:3]
	s_setprio 0
	s_add_i32 s11, s11, 0x8000
	s_add_u32 s6, s6, 0x80
	s_addc_u32 s7, s7, 0
	s_addk_i32 s3, 0x4000
	s_cmpk_lg_i32 s6, 0x780
	s_cbranch_scc1 .LBB0_660
	v_lshlrev_b32_e32 v86, 1, v86
	v_lshlrev_b32_e32 v85, 1, v85
	s_waitcnt vmcnt(0) lgkmcnt(0)
	s_barrier
;     ...
; #pragma unroll 1
;     for (int kt = 0; kt < nk - 1; ++kt) {
;       asm volatile("s_waitcnt vmcnt(0) lgkmcnt(0)" ::: "memory");
;       __builtin_amdgcn_s_barrier();
;       asm volatile("" ::: "memory");
;       G3_STEP(kt, true)
;     }
;     asm volatile("s_waitcnt vmcnt(0) lgkmcnt(0)" ::: "memory");
;     __builtin_amdgcn_s_barrier();
;     asm volatile("" ::: "memory");
;     G3_STEP(nk - 1, false)
; DI void inproj_tile(const Params& P, int l, int it, u16* sA, u16* sB) {
;     ...
;   __syncthreads();
; #pragma unroll
;   for (int mi = 0; mi < 4; ++mi)
; #pragma unroll
;     for (int ni = 0; ni < 4; ++ni)
; #pragma unroll
;       for (int j = 0; j < 4; ++j) sA[(wm * 64 + 16 * mi + 4 * quad + j) * 136 + wn * 64 + 16 * ni + r16] = f2bf(acc[mi][ni][j]);
	v_add3_u32 v76, v86, v84, v83
	v_add3_u32 v98, v86, v82, v83
	v_add3_u32 v84, v85, v84, v83
	v_add3_u32 v126, v85, v82, v83
	ds_read_b128 v[64:67], v76 offset:32768
	ds_read_b128 v[68:71], v76 offset:34816
	ds_read_b128 v[72:75], v76 offset:36864
	ds_read_b128 v[76:79], v76 offset:38912
	ds_read_b128 v[86:89], v98 offset:49152
	ds_read_b128 v[90:93], v98 offset:51200
	ds_read_b128 v[94:97], v98 offset:53248
	ds_read_b128 v[98:101], v98 offset:55296
	ds_read_b128 v[102:105], v84 offset:32768
	ds_read_b128 v[106:109], v84 offset:34816
	ds_read_b128 v[110:113], v84 offset:36864
	ds_read_b128 v[114:117], v84 offset:38912
	ds_read_b128 v[82:85], v126 offset:49152
	ds_read_b128 v[118:121], v126 offset:51200
	ds_read_b128 v[122:125], v126 offset:53248
	ds_read_b128 v[126:129], v126 offset:55296
	s_setprio 1
	s_waitcnt lgkmcnt(11)
	v_mfma_f32_16x16x32_bf16 v[60:63], v[64:67], v[86:89], v[60:63]
	s_waitcnt lgkmcnt(10)
	v_mfma_f32_16x16x32_bf16 v[56:59], v[64:67], v[90:93], v[56:59]
	s_waitcnt lgkmcnt(9)
	v_mfma_f32_16x16x32_bf16 v[52:55], v[64:67], v[94:97], v[52:55]
	s_waitcnt lgkmcnt(8)
	v_mfma_f32_16x16x32_bf16 v[48:51], v[64:67], v[98:101], v[48:51]
	v_mfma_f32_16x16x32_bf16 v[44:47], v[68:71], v[86:89], v[44:47]
	v_mfma_f32_16x16x32_bf16 v[40:43], v[68:71], v[90:93], v[40:43]
	v_mfma_f32_16x16x32_bf16 v[36:39], v[68:71], v[94:97], v[36:39]
	v_mfma_f32_16x16x32_bf16 v[32:35], v[68:71], v[98:101], v[32:35]
	v_mfma_f32_16x16x32_bf16 v[28:31], v[72:75], v[86:89], v[28:31]
	v_mfma_f32_16x16x32_bf16 v[24:27], v[72:75], v[90:93], v[24:27]
	v_mfma_f32_16x16x32_bf16 v[20:23], v[72:75], v[94:97], v[20:23]
	v_mfma_f32_16x16x32_bf16 v[16:19], v[72:75], v[98:101], v[16:19]
	v_mfma_f32_16x16x32_bf16 v[12:15], v[76:79], v[86:89], v[12:15]
	v_mfma_f32_16x16x32_bf16 v[8:11], v[76:79], v[90:93], v[8:11]
	v_mfma_f32_16x16x32_bf16 v[0:3], v[76:79], v[98:101], v[0:3]
	v_mfma_f32_16x16x32_bf16 v[4:7], v[76:79], v[94:97], v[4:7]
	s_waitcnt lgkmcnt(0)
	v_mfma_f32_16x16x32_bf16 v[0:3], v[114:117], v[126:129], v[0:3]
	v_mfma_f32_16x16x32_bf16 v[60:63], v[102:105], v[82:85], v[60:63]
	v_mfma_f32_16x16x32_bf16 v[56:59], v[102:105], v[118:121], v[56:59]
	v_mfma_f32_16x16x32_bf16 v[52:55], v[102:105], v[122:125], v[52:55]
	v_mfma_f32_16x16x32_bf16 v[48:51], v[102:105], v[126:129], v[48:51]
	v_mfma_f32_16x16x32_bf16 v[44:47], v[106:109], v[82:85], v[44:47]
	v_mfma_f32_16x16x32_bf16 v[40:43], v[106:109], v[118:121], v[40:43]
	v_mfma_f32_16x16x32_bf16 v[36:39], v[106:109], v[122:125], v[36:39]
	v_mfma_f32_16x16x32_bf16 v[32:35], v[106:109], v[126:129], v[32:35]
	v_mfma_f32_16x16x32_bf16 v[28:31], v[110:113], v[82:85], v[28:31]
	v_mfma_f32_16x16x32_bf16 v[24:27], v[110:113], v[118:121], v[24:27]
	v_mfma_f32_16x16x32_bf16 v[20:23], v[110:113], v[122:125], v[20:23]
	v_mfma_f32_16x16x32_bf16 v[16:19], v[110:113], v[126:129], v[16:19]
	v_mfma_f32_16x16x32_bf16 v[12:15], v[114:117], v[82:85], v[12:15]
	v_mfma_f32_16x16x32_bf16 v[8:11], v[114:117], v[118:121], v[8:11]
	v_mfma_f32_16x16x32_bf16 v[4:7], v[114:117], v[122:125], v[4:7]
	s_setprio 0
	v_lshrrev_b32_e32 v64, 2, v80
	v_and_b32_e32 v64, 12, v64
	s_mov_b32 s1, 0xfffffc0
	v_and_or_b32 v64, v81, s1, v64
	s_movk_i32 s1, 0x110
	v_and_b32_e32 v65, 0x4f, v80
	v_mul_lo_u32 v64, v64, s1
	v_cvt_pk_bf16_f32 v60, v60, s0
	v_lshl_add_u32 v64, v65, 1, v64
	v_cvt_pk_bf16_f32 v56, v56, s0
	v_cvt_pk_bf16_f32 v52, v52, s0
	v_cvt_pk_bf16_f32 v48, v48, s0
	v_cvt_pk_bf16_f32 v44, v44, s0
	v_cvt_pk_bf16_f32 v40, v40, s0
	v_cvt_pk_bf16_f32 v36, v36, s0
	v_cvt_pk_bf16_f32 v32, v32, s0
	v_cvt_pk_bf16_f32 v28, v28, s0
	v_cvt_pk_bf16_f32 v24, v24, s0
	v_cvt_pk_bf16_f32 v20, v20, s0
	v_cvt_pk_bf16_f32 v16, v16, s0
	v_cvt_pk_bf16_f32 v12, v12, s0
	v_cvt_pk_bf16_f32 v8, v8, s0
	v_cvt_pk_bf16_f32 v4, v4, s0
	v_cvt_pk_bf16_f32 v0, v0, s0
	s_add_u32 s1, s70, s4
	s_barrier
; DI int TID() { int t = threadIdx.x; asm volatile("" : "+v"(t)); return t; }
; template <int NCOLS>
; DI void store_tile_bf16(const u16* sC, u16* gdst, long ld, int rows_valid) {
;   constexpr int CPR = NCOLS / 8, LS = NCOLS + 8;
;   const int tid = TID();
; #pragma unroll
;   for (int q = 0; q < (128 * CPR) / 256; ++q) {
;     const int c = tid + 256 * q, row = c / CPR, ch = c % CPR;
;     if (row < rows_valid) *(uint4*)(gdst + (long)row * ld + ch * 8) = *(const uint4*)(sC + row * LS + ch * 8);
;   }
; }
; DI void inproj_tile(const Params& P, int l, int it, u16* sA, u16* sB) {
;     ...
;   __syncthreads();
; #pragma unroll
;   for (int mi = 0; mi < 4; ++mi)
; #pragma unroll
;     for (int ni = 0; ni < 4; ++ni)
; #pragma unroll
;       for (int j = 0; j < 4; ++j) sA[(wm * 64 + 16 * mi + 4 * quad + j) * 136 + wn * 64 + 16 * ni + r16] = f2bf(acc[mi][ni][j]);
;   __syncthreads();
;   store_tile_bf16<128>(sA, PROJ + (long)mt * 128 * PW + nt * 128, PW, 128);
	ds_write_b16 v64, v60
	v_cvt_pk_bf16_f32 v60, v61, s0
	ds_write_b16 v64, v56 offset:32
	v_cvt_pk_bf16_f32 v56, v57, s0
	ds_write_b16 v64, v52 offset:64
	v_cvt_pk_bf16_f32 v52, v53, s0
	ds_write_b16 v64, v48 offset:96
	v_cvt_pk_bf16_f32 v48, v49, s0
	ds_write_b16 v64, v44 offset:4352
	v_cvt_pk_bf16_f32 v44, v45, s0
	ds_write_b16 v64, v40 offset:4384
	v_cvt_pk_bf16_f32 v40, v41, s0
	ds_write_b16 v64, v36 offset:4416
	v_cvt_pk_bf16_f32 v36, v37, s0
	ds_write_b16 v64, v32 offset:4448
	v_cvt_pk_bf16_f32 v32, v33, s0
	ds_write_b16 v64, v28 offset:8704
	v_cvt_pk_bf16_f32 v28, v29, s0
	ds_write_b16 v64, v24 offset:8736
	v_cvt_pk_bf16_f32 v24, v25, s0
	ds_write_b16 v64, v20 offset:8768
	v_cvt_pk_bf16_f32 v20, v21, s0
	ds_write_b16 v64, v16 offset:8800
	v_cvt_pk_bf16_f32 v16, v17, s0
	ds_write_b16 v64, v12 offset:13056
	v_cvt_pk_bf16_f32 v12, v13, s0
	ds_write_b16 v64, v8 offset:13088
	v_cvt_pk_bf16_f32 v8, v9, s0
	ds_write_b16 v64, v4 offset:13120
	v_cvt_pk_bf16_f32 v4, v5, s0
	ds_write_b16 v64, v0 offset:13152
	v_cvt_pk_bf16_f32 v0, v1, s0
	s_addc_u32 s3, s71, s5
	s_mul_hi_i32 s4, s2, 0xb0000
	s_mul_i32 s2, s2, 0xb0000
	ds_write_b16 v64, v60 offset:272
	v_cvt_pk_bf16_f32 v60, v62, s0
	ds_write_b16 v64, v56 offset:304
	v_cvt_pk_bf16_f32 v56, v58, s0
	ds_write_b16 v64, v52 offset:336
	v_cvt_pk_bf16_f32 v52, v54, s0
	ds_write_b16 v64, v48 offset:368
	v_cvt_pk_bf16_f32 v48, v50, s0
	ds_write_b16 v64, v44 offset:4624
	v_cvt_pk_bf16_f32 v44, v46, s0
	ds_write_b16 v64, v40 offset:4656
	v_cvt_pk_bf16_f32 v40, v42, s0
	ds_write_b16 v64, v36 offset:4688
	v_cvt_pk_bf16_f32 v36, v38, s0
	ds_write_b16 v64, v32 offset:4720
	v_cvt_pk_bf16_f32 v32, v34, s0
	ds_write_b16 v64, v28 offset:8976
	v_cvt_pk_bf16_f32 v28, v30, s0
	ds_write_b16 v64, v24 offset:9008
	v_cvt_pk_bf16_f32 v24, v26, s0
	ds_write_b16 v64, v20 offset:9040
	v_cvt_pk_bf16_f32 v20, v22, s0
	ds_write_b16 v64, v16 offset:9072
	v_cvt_pk_bf16_f32 v16, v18, s0
	ds_write_b16 v64, v12 offset:13328
	v_cvt_pk_bf16_f32 v12, v14, s0
	ds_write_b16 v64, v8 offset:13360
	v_cvt_pk_bf16_f32 v8, v10, s0
	ds_write_b16 v64, v4 offset:13392
	v_cvt_pk_bf16_f32 v4, v6, s0
	ds_write_b16 v64, v0 offset:13424
	v_cvt_pk_bf16_f32 v0, v2, s0
	s_add_u32 s2, s1, s2
	ds_write_b16 v64, v60 offset:544
	v_cvt_pk_bf16_f32 v60, v63, s0
	ds_write_b16 v64, v56 offset:576
	v_cvt_pk_bf16_f32 v56, v59, s0
	ds_write_b16 v64, v52 offset:608
	v_cvt_pk_bf16_f32 v52, v55, s0
	ds_write_b16 v64, v48 offset:640
	v_cvt_pk_bf16_f32 v48, v51, s0
	ds_write_b16 v64, v44 offset:4896
	v_cvt_pk_bf16_f32 v44, v47, s0
	ds_write_b16 v64, v40 offset:4928
	v_cvt_pk_bf16_f32 v40, v43, s0
	ds_write_b16 v64, v36 offset:4960
	v_cvt_pk_bf16_f32 v36, v39, s0
	ds_write_b16 v64, v32 offset:4992
	v_cvt_pk_bf16_f32 v32, v35, s0
	ds_write_b16 v64, v28 offset:9248
	v_cvt_pk_bf16_f32 v28, v31, s0
	ds_write_b16 v64, v24 offset:9280
	v_cvt_pk_bf16_f32 v24, v27, s0
	ds_write_b16 v64, v20 offset:9312
	v_cvt_pk_bf16_f32 v20, v23, s0
	ds_write_b16 v64, v16 offset:9344
	v_cvt_pk_bf16_f32 v16, v19, s0
	ds_write_b16 v64, v12 offset:13600
	v_cvt_pk_bf16_f32 v12, v15, s0
	ds_write_b16 v64, v8 offset:13632
	v_cvt_pk_bf16_f32 v8, v11, s0
	ds_write_b16 v64, v4 offset:13664
	v_cvt_pk_bf16_f32 v4, v7, s0
	ds_write_b16 v64, v0 offset:13696
	v_cvt_pk_bf16_f32 v0, v3, s0
	s_addc_u32 s3, s3, s4
	s_lshl_b32 s0, s0, 7
	s_ashr_i32 s1, s0, 31
	s_lshl_b64 s[0:1], s[0:1], 1
	s_add_u32 s0, s2, s0
	s_addc_u32 s1, s3, s1
	ds_write_b16 v64, v0 offset:13968
	s_add_u32 s0, s0, 0x4000000
	v_mov_b32_e32 v0, v160
	s_movk_i32 s2, 0x800
	ds_write_b16 v64, v60 offset:816
	ds_write_b16 v64, v56 offset:848
	ds_write_b16 v64, v52 offset:880
	ds_write_b16 v64, v48 offset:912
	ds_write_b16 v64, v44 offset:5168
	ds_write_b16 v64, v40 offset:5200
	ds_write_b16 v64, v36 offset:5232
	ds_write_b16 v64, v32 offset:5264
	ds_write_b16 v64, v28 offset:9520
	ds_write_b16 v64, v24 offset:9552
	ds_write_b16 v64, v20 offset:9584
	ds_write_b16 v64, v16 offset:9616
	ds_write_b16 v64, v12 offset:13872
	ds_write_b16 v64, v8 offset:13904
	ds_write_b16 v64, v4 offset:13936
	s_waitcnt lgkmcnt(0)
	s_barrier
	s_addc_u32 s1, s1, 0
	s_nop 0
	v_cmp_gt_i32_e32 vcc, s2, v0
	s_and_saveexec_b64 s[2:3], vcc
	s_cbranch_execz .LBB0_663
	v_ashrrev_i32_e32 v1, 31, v0
	v_lshrrev_b32_e32 v1, 28, v1
	v_add_u32_e32 v1, v0, v1
	v_ashrrev_i32_e32 v6, 4, v1
	v_and_b32_e32 v1, -16, v1
	s_movk_i32 s4, 0x110
	v_sub_u32_e32 v1, v0, v1
	v_mul_lo_u32 v4, v6, s4
	v_lshlrev_b32_e32 v2, 3, v1
	v_lshl_add_u32 v1, v1, 4, v4
	v_mov_b64_e32 v[4:5], s[0:1]
	s_movk_i32 s4, 0x1600
	v_ashrrev_i32_e32 v3, 31, v2
	v_mad_i64_i32 v[4:5], s[4:5], v6, s4, v[4:5]
	v_lshl_add_u64 v[6:7], v[2:3], 1, v[4:5]
	ds_read_b128 v[2:5], v1
	s_waitcnt lgkmcnt(0)
	global_store_dwordx4 v[6:7], v[2:5], off sc1
